# v29 + attention loops: one static s_setprio 1 for waves 4-7 per item, all per-segment setprio flips deleted
# baseline (speedup 1.0000x reference)
; __device__ __forceinline__ int my_tid() { int t = threadIdx.x; asm volatile("" : "+v"(t)); return t; }
; template <int TYPE  >
; __device__ __forceinline__ void attn_item(const Params& P, const int b, const int h, const int qt, LAS unsigned char* lds) {
;     ...
;     const int tid = my_tid(), wid = __builtin_amdgcn_readfirstlane(tid >> 6), lane = tid & 63, l32 = lane & 31, hh = lane >> 5;
;     unsigned char* ws = P.ws;
;     const int bh = b * 8 + h;
;     const int tq = qt * 256 + wid * 32 + l32;
;     const size_t tokq = (size_t)b * 2048 + tq;
;     const int NT = 4 * qt + 4, wlast = 4 * qt + (wid >> 1);
.LBB0_1088:
	v_readfirstlane_b32 s100, v208
	s_nop 3
	s_cmp_ge_u32 s100, 0x100
	s_cbranch_scc0 .Lprio_done
	s_setprio 1

; __device__ __forceinline__ float log2_(float x) { return __builtin_amdgcn_logf(x); }
; __device__ __forceinline__ float exp2_negabs(float x) { float r; asm("v_exp_f32 %0, -|%1|\n\ts_nop 1" : "=v"(r) : "v"(x)); return r; }
; #define AT_RV(vf, mb) do { vf[0] = *(const LAS bf16x8*)(lds + vb + (mb) * 4096); vf[1] = *(const LAS bf16x8*)(lds + (vb ^ 32u) + (mb) * 4096); \
;                 vf[2] = *(const LAS bf16x8*)(lds + (vb ^ 64u) + (mb) * 4096); vf[3] = *(const LAS bf16x8*)(lds + (vb ^ 96u) + (mb) * 4096); } while (0)
; __device__ __forceinline__ void sb_sub(f32x16& s, float& carry, const int hh) {
;     float w[16];
; #pragma unroll
;     for (int i = 0; i < 16; ++i) { const float z = s[i]; const float t = log2_(1.f + exp2_negabs(z));
;         w[i] = -(__builtin_fmaxf(z, 0.f) + t); }
; template <int TYPE  >
; __device__ __forceinline__ void attn_item(const Params& P, const int b, const int h, const int qt, LAS unsigned char* lds) {
;     ...
;             if (!have_s) { AT_QK(so); }
;             const unsigned vb = a0v + so;
;             bf16x8 vf0[4], vf1[4], vf2[4], vf3[4];
;     ...
;             AT_RV(vf0, 0);
;             __builtin_amdgcn_sched_barrier(0);
;             const bool diag = (kt == wlast);
;             const int key0 = kt * 64 + 8 * hh;
;             if (TYPE == 2) {
;                 if (diag) {
; #pragma unroll
;                     for (int i = 0; i < 16; ++i) { const int key = key0 + 16 * (i >> 3) + (i & 7); if (key >= tq) s0[i] = -1e30f; if (key + 32 >= tq) s1[i] = -1e30f; } }
;                 sb_sub(s1, carry, hh); sb_sub(s0, carry, hh);
.LBB0_1107:
	v_add_u32_e32 v0, s29, v184
	v_add_u32_e32 v6, 0, v0
	v_xad_u32 v14, v0, 32, 0
	ds_read_b128 v[2:5], v6
	ds_read_b128 v[6:9], v6 offset:8192
	ds_read_b128 v[10:13], v14
	ds_read_b128 v[144:147], v14 offset:8192
	v_xad_u32 v14, v0, 64, 0
	ds_read_b128 v[158:161], v14
	ds_read_b128 v[176:179], v14 offset:8192
	v_xor_b32_e32 v14, 0x60, v0
	v_add_u32_e32 v14, 0, v14
	ds_read_b128 v[188:191], v14
	ds_read_b128 v[192:195], v14 offset:8192
	v_xor_b32_e32 v14, 0x80, v0
	v_add_u32_e32 v14, 0, v14
	ds_read_b128 v[196:199], v14
	ds_read_b128 v[200:203], v14 offset:8192
	v_xor_b32_e32 v14, 0xa0, v0
	v_add_u32_e32 v14, 0, v14
	ds_read_b128 v[204:207], v14
	ds_read_b128 v[226:229], v14 offset:8192
	v_xor_b32_e32 v14, 0xc0, v0
	v_xor_b32_e32 v0, 0xe0, v0
	v_add_u32_e32 v14, 0, v14
	v_add_u32_e32 v0, 0, v0
	ds_read_b128 v[230:233], v14
	ds_read_b128 v[234:237], v14 offset:8192
	ds_read_b128 v[238:241], v0
	ds_read_b128 v[242:245], v0 offset:8192
	s_waitcnt lgkmcnt(0)
	v_mfma_f32_32x32x16_bf16 v[80:95], v[2:5], v[112:115], 0
	v_mfma_f32_32x32x16_bf16 v[96:111], v[6:9], v[112:115], 0
	v_mfma_f32_32x32x16_bf16 v[80:95], v[10:13], v[116:119], v[80:95]
	v_mfma_f32_32x32x16_bf16 v[96:111], v[144:147], v[116:119], v[96:111]
	v_mfma_f32_32x32x16_bf16 v[80:95], v[158:161], v[120:123], v[80:95]
	v_mfma_f32_32x32x16_bf16 v[96:111], v[176:179], v[120:123], v[96:111]
	v_mfma_f32_32x32x16_bf16 v[80:95], v[188:191], v[124:127], v[80:95]
	v_mfma_f32_32x32x16_bf16 v[96:111], v[192:195], v[124:127], v[96:111]
	v_mfma_f32_32x32x16_bf16 v[80:95], v[196:199], v[128:131], v[80:95]
	v_mfma_f32_32x32x16_bf16 v[96:111], v[200:203], v[128:131], v[96:111]
	v_mfma_f32_32x32x16_bf16 v[80:95], v[204:207], v[132:135], v[80:95]
	v_mfma_f32_32x32x16_bf16 v[96:111], v[226:229], v[132:135], v[96:111]
	v_mfma_f32_32x32x16_bf16 v[80:95], v[230:233], v[136:139], v[80:95]
	v_mfma_f32_32x32x16_bf16 v[96:111], v[234:237], v[136:139], v[96:111]
	v_mfma_f32_32x32x16_bf16 v[80:95], v[238:241], v[140:143], v[80:95]
	v_mfma_f32_32x32x16_bf16 v[96:111], v[242:245], v[140:143], v[96:111]
	v_add_u32_e32 v10, s29, v186
	v_add_u32_e32 v0, s29, v185
	v_xor_b32_e32 v11, 64, v10
	v_add_u32_e32 v0, 0, v0
	v_xor_b32_e32 v2, 32, v10
	v_add_u32_e32 v188, 0, v11
	v_xor_b32_e32 v10, 0x60, v10
	s_nop 7
	s_nop 7
	s_nop 3
	v_add_u32_e32 v187, 0, v2
	ds_read_b128 v[6:9], v0 offset:16384
	ds_read_b128 v[2:5], v187
	v_add_u32_e32 v189, 0, v10
	ds_read_b128 v[144:147], v188
	ds_read_b128 v[10:13], v189
	s_cmp_lg_u32 s26, s17
	s_cbranch_scc1 .LBB0_1109
	v_cndmask_b32_e64 v95, v223, v95, s[38:39]
	v_cndmask_b32_e64 v94, v223, v94, s[42:43]
	v_cndmask_b32_e64 v93, v223, v93, s[44:45]
	v_cndmask_b32_e64 v92, v223, v92, s[46:47]
	v_cndmask_b32_e64 v91, v223, v91, s[48:49]
	v_cndmask_b32_e64 v90, v223, v90, s[50:51]
	v_cndmask_b32_e64 v89, v223, v89, s[52:53]
	v_cndmask_b32_e64 v88, v223, v88, s[54:55]
	v_cndmask_b32_e64 v87, v223, v87, s[56:57]
	v_cndmask_b32_e64 v86, v223, v86, s[58:59]
	v_cndmask_b32_e64 v85, v223, v85, s[60:61]
	v_cndmask_b32_e64 v84, v223, v84, s[62:63]
	v_cndmask_b32_e64 v83, v223, v83, s[4:5]
	v_cndmask_b32_e64 v82, v223, v82, s[64:65]
	v_cndmask_b32_e64 v81, v223, v81, s[66:67]
	v_cndmask_b32_e64 v80, v223, v80, s[68:69]
	v_cndmask_b32_e64 v111, v223, v111, s[40:41]
	v_cndmask_b32_e64 v110, v223, v110, s[70:71]
	v_cndmask_b32_e64 v109, v223, v109, s[72:73]
	v_cndmask_b32_e64 v108, v223, v108, s[6:7]
	v_cndmask_b32_e64 v107, v223, v107, s[74:75]
	v_cndmask_b32_e64 v106, v223, v106, s[76:77]
	v_cndmask_b32_e64 v105, v223, v105, s[78:79]
	v_cndmask_b32_e64 v104, v223, v104, s[80:81]
	v_cndmask_b32_e64 v103, v223, v103, s[82:83]
	v_cndmask_b32_e64 v102, v223, v102, s[84:85]
	v_cndmask_b32_e64 v101, v223, v101, s[86:87]
	v_cndmask_b32_e64 v100, v223, v100, s[88:89]
	v_cndmask_b32_e64 v99, v223, v99, s[90:91]
	v_cndmask_b32_e64 v98, v223, v98, s[92:93]
	v_cndmask_b32_e64 v97, v223, v97, s[94:95]
	v_cndmask_b32_e64 v96, v223, v96, s[96:97]
.LBB0_1109:
	v_max_f32_e32 v159, 0, v98
	v_exp_f32 v157, -|v99|
	s_nop 0
	v_add_f32_e32 v157, 1.0, v157
	v_log_f32_e32 v161, v157
	v_max_f32_e32 v177, 0, v99
	v_exp_f32 v157, -|v100|
	v_max_f32_e32 v158, 0, v96
	v_add_f32_e32 v157, 1.0, v157
	v_log_f32_e32 v178, v157
	v_max_f32_e32 v180, 0, v100
	v_exp_f32 v157, -|v101|
	v_exp_f32 v15, -|v97|
	v_exp_f32 v14, -|v96|
	s_nop 0
	v_add_f32_e32 v157, 1.0, v157
	v_log_f32_e32 v190, v157
	v_max_f32_e32 v192, 0, v101
	v_exp_f32 v157, -|v102|
	v_add_f32_e32 v15, 1.0, v15
	v_add_f32_e32 v157, 1.0, v157
	v_log_f32_e32 v179, v157
	v_max_f32_e32 v181, 0, v102
	v_exp_f32 v157, -|v103|
	v_log_f32_e32 v160, v15
	v_add_f32_e32 v157, 1.0, v157
	v_log_f32_e32 v191, v157
	v_max_f32_e32 v193, 0, v103
	v_exp_f32 v157, -|v104|
	s_nop 0
	v_add_f32_e32 v157, 1.0, v157
	v_log_f32_e32 v194, v157
	v_max_f32_e32 v196, 0, v104
	v_exp_f32 v157, -|v105|
	v_max_f32_e32 v176, 0, v97
	v_add_f32_e32 v157, 1.0, v157
	v_log_f32_e32 v198, v157
	v_max_f32_e32 v200, 0, v105
	v_exp_f32 v157, -|v106|
	v_exp_f32 v15, -|v98|
	v_add_f32_e32 v14, 1.0, v14
	v_add_f32_e32 v157, 1.0, v157
	v_log_f32_e32 v195, v157
	v_max_f32_e32 v197, 0, v106
	v_exp_f32 v157, -|v107|
	v_add_f32_e32 v15, 1.0, v15
	v_add_f32_e32 v157, 1.0, v157
	v_log_f32_e32 v199, v157
	v_max_f32_e32 v201, 0, v107
	v_exp_f32 v157, -|v108|
	v_log_f32_e32 v14, v14
	v_add_f32_e32 v157, 1.0, v157
	v_log_f32_e32 v202, v157
	v_max_f32_e32 v204, 0, v108
	v_exp_f32 v157, -|v109|
	v_log_f32_e32 v15, v15
	v_add_f32_e32 v157, 1.0, v157
	v_log_f32_e32 v206, v157
	v_max_f32_e32 v214, 0, v109
	v_exp_f32 v157, -|v110|
	v_pk_add_f32 v[14:15], v[158:159], v[14:15]
	v_add_f32_e32 v157, 1.0, v157
; __device__ __forceinline__ float exp2_(float x) { return __builtin_amdgcn_exp2f(x); }
; __device__ __forceinline__ float log2_(float x) { return __builtin_amdgcn_logf(x); }
; __device__ __forceinline__ float swap_partner(float x, int hh) { auto rr = __builtin_amdgcn_permlane32_swap(__float_as_uint(x), __float_as_uint(x), false, false); return __uint_as_float(hh ? rr[0] : rr[1]); }
; __device__ __forceinline__ float exp2_negabs(float x) { float r; asm("v_exp_f32 %0, -|%1|\n\ts_nop 1" : "=v"(r) : "v"(x)); return r; }
; __device__ __forceinline__ void sb_sub(f32x16& s, float& carry, const int hh) {
;     float w[16];
; #pragma unroll
;     for (int i = 0; i < 16; ++i) { const float z = s[i]; const float t = log2_(1.f + exp2_negabs(z));
;         w[i] = -(__builtin_fmaxf(z, 0.f) + t); }
;     const float GA = ((w[0] + w[1]) + (w[2] + w[3])) + ((w[4] + w[5]) + (w[6] + w[7])), GB = ((w[8] + w[9]) + (w[10] + w[11])) + ((w[12] + w[13]) + (w[14] + w[15]));
;     const float GAp = swap_partner(GA, hh), GBp = swap_partner(GB, hh);
;     float a = carry + (hh == 0 ? GBp : 0.f);
; #pragma unroll
;     for (int i = 15; i >= 8; --i) { const float wi = w[i]; s[i] = exp2_((s[i] + wi) + a); a += wi; }
;     a = carry + GB + GBp + (hh == 0 ? GAp : 0.f);
; #pragma unroll
;     for (int i = 7; i >= 0; --i) { const float wi = w[i]; s[i] = exp2_((s[i] + wi) + a); a += wi; }
	v_log_f32_e32 v203, v157
	v_max_f32_e32 v205, 0, v110
	v_exp_f32 v157, -|v111|
	v_pk_add_f32 v[158:159], v[176:177], v[160:161]
	v_add_f32_e32 v157, 1.0, v157
	v_log_f32_e32 v207, v157
	v_pk_add_f32 v[176:177], v[192:193], v[190:191]
	v_sub_f32_e32 v225, v103, v177
	v_exp_f32 v103, -|v80|
	v_max_f32_e32 v215, 0, v111
	v_add_f32_e32 v103, 1.0, v103
	v_pk_add_f32 v[192:193], v[196:197], v[194:195]
	v_pk_add_f32 v[194:195], v[200:201], v[198:199]
	v_pk_add_f32 v[198:199], v[204:205], v[202:203]
	v_log_f32_e32 v204, v103
	v_pk_add_f32 v[200:201], v[214:215], v[206:207]
	v_max_f32_e32 v206, 0, v80
	v_exp_f32 v103, -|v81|
	v_pk_add_f32 v[160:161], v[180:181], v[178:179]
	v_add_f32_e32 v103, 1.0, v103
	v_log_f32_e32 v205, v103
	v_max_f32_e32 v207, 0, v81
	v_exp_f32 v103, -|v82|
	v_pk_add_f32 v[196:197], v[194:195], v[192:193] neg_lo:[1,1] neg_hi:[1,1]
	v_add_f32_e32 v103, 1.0, v103
	v_log_f32_e32 v214, v103
	v_max_f32_e32 v228, 0, v82
	v_exp_f32 v103, -|v83|
	v_pk_add_f32 v[202:203], v[200:201], v[198:199] neg_lo:[1,1] neg_hi:[1,1]
	v_add_f32_e32 v103, 1.0, v103
	v_log_f32_e32 v215, v103
	v_max_f32_e32 v229, 0, v83
	v_exp_f32 v103, -|v84|
	v_pk_add_f32 v[196:197], v[196:197], v[196:197] op_sel:[0,1] op_sel_hi:[1,0]
	v_add_f32_e32 v103, 1.0, v103
	v_log_f32_e32 v230, v103
	v_max_f32_e32 v232, 0, v84
	v_exp_f32 v103, -|v85|
	v_pk_add_f32 v[202:203], v[202:203], v[202:203] op_sel:[0,1] op_sel_hi:[1,0]
	v_add_f32_e32 v103, 1.0, v103
	v_log_f32_e32 v231, v103
	v_max_f32_e32 v233, 0, v85
	v_exp_f32 v103, -|v86|
	v_pk_add_f32 v[230:231], v[232:233], v[230:231]
	v_add_f32_e32 v103, 1.0, v103
	v_log_f32_e32 v234, v103
	v_max_f32_e32 v236, 0, v86
	v_exp_f32 v103, -|v87|
	v_sub_f32_e64 v197, -v231, v230
	v_add_f32_e32 v103, 1.0, v103
	v_log_f32_e32 v235, v103
	v_max_f32_e32 v237, 0, v87
	v_exp_f32 v103, -|v88|
	v_pk_add_f32 v[234:235], v[236:237], v[234:235]
	v_add_f32_e32 v103, 1.0, v103
	v_log_f32_e32 v178, v103
	v_max_f32_e32 v180, 0, v88
	v_exp_f32 v103, -|v89|
	v_sub_f32_e64 v203, -v235, v234
	v_add_f32_e32 v103, 1.0, v103
	v_log_f32_e32 v238, v103
	v_max_f32_e32 v240, 0, v89
	v_exp_f32 v103, -|v90|
	v_pk_add_f32 v[196:197], v[196:197], v[202:203]
	v_add_f32_e32 v103, 1.0, v103
	v_log_f32_e32 v179, v103
	v_max_f32_e32 v181, 0, v90
	v_exp_f32 v103, -|v91|
	v_pk_add_f32 v[178:179], v[180:181], v[178:179]
	v_add_f32_e32 v103, 1.0, v103
	v_log_f32_e32 v239, v103
	v_max_f32_e32 v241, 0, v91
	v_exp_f32 v103, -|v92|
	v_pk_add_f32 v[180:181], v[240:241], v[238:239]
	v_add_f32_e32 v103, 1.0, v103
	v_log_f32_e32 v242, v103
	v_max_f32_e32 v244, 0, v92
	v_exp_f32 v103, -|v93|
	v_sub_f32_e32 v236, v87, v235
	v_add_f32_e32 v103, 1.0, v103
	v_log_f32_e32 v246, v103
	v_max_f32_e32 v248, 0, v93
	v_exp_f32 v103, -|v94|
	v_mov_b32_e32 v87, v196
	v_add_f32_e32 v103, 1.0, v103
	v_log_f32_e32 v243, v103
	v_max_f32_e32 v245, 0, v94
	v_exp_f32 v103, -|v95|
	v_pk_add_f32 v[240:241], v[244:245], v[242:243]
	v_add_f32_e32 v103, 1.0, v103
	v_log_f32_e32 v247, v103
	v_max_f32_e32 v249, 0, v95
	v_sub_f32_e32 v157, v111, v201
	v_pk_add_f32 v[242:243], v[248:249], v[246:247]
	v_mov_b32_e32 v202, v199
	v_pk_add_f32 v[244:245], v[242:243], v[240:241] neg_lo:[1,1] neg_hi:[1,1]
	v_sub_f32_e32 v252, v95, v243
	v_mov_b32_e32 v95, v196
	v_pk_add_f32 v[244:245], v[244:245], v[244:245] op_sel_hi:[0,1]
	s_nop 0
	v_permlane32_swap_b32_e32 v87, v95
	v_cndmask_b32_e64 v244, v87, v95, s[8:9]
	v_cndmask_b32_e64 v87, 0, v244, s[8:9]
	v_add_f32_e32 v111, v156, v87
	v_mov_b32_e32 v203, v201
	v_add_f32_e32 v87, v157, v111
	v_pk_add_f32 v[110:111], v[110:111], v[202:203] neg_lo:[0,1] neg_hi:[0,1]
	v_exp_f32_e32 v232, v87
	v_add_f32_e32 v87, v110, v111
	v_mov_b32_e32 v110, v109
	v_mov_b32_e32 v201, v199
	v_pk_add_f32 v[110:111], v[110:111], v[200:201] neg_lo:[0,1] neg_hi:[0,1]
	v_exp_f32_e32 v202, v87
	v_add_f32_e32 v87, v110, v111
	v_mov_b32_e32 v109, v111
	v_mov_b32_e32 v110, v198
	v_mov_b32_e32 v111, v200
	v_pk_add_f32 v[108:109], v[108:109], v[110:111] neg_lo:[0,1] neg_hi:[0,1]
	v_exp_f32_e32 v201, v87
	v_add_f32_e32 v87, v108, v109
	v_mov_b32_e32 v108, v107
	v_pk_mov_b32 v[110:111], v[194:195], v[198:199] op_sel:[1,0]
	v_exp_f32_e32 v200, v87
	v_pk_add_f32 v[108:109], v[108:109], v[110:111] neg_lo:[0,1] neg_hi:[0,1]
	v_pk_add_f32 v[226:227], v[158:159], v[14:15] neg_lo:[1,1] neg_hi:[1,1]
	v_add_f32_e32 v87, v108, v109
	v_mov_b32_e32 v107, v109
	v_mov_b32_e32 v108, v193
	v_mov_b32_e32 v109, v195
	v_pk_add_f32 v[106:107], v[106:107], v[108:109] neg_lo:[0,1] neg_hi:[0,1]
	v_exp_f32_e32 v198, v87
	v_add_f32_e32 v87, v106, v107
	v_mov_b32_e32 v106, v105
	v_mov_b32_e32 v195, v193
	v_pk_add_f32 v[190:191], v[176:177], v[160:161] neg_lo:[1,1] neg_hi:[1,1]
	v_pk_add_f32 v[106:107], v[106:107], v[194:195] neg_lo:[0,1] neg_hi:[0,1]
	v_pk_add_f32 v[226:227], v[226:227], v[226:227] op_sel:[0,1] op_sel_hi:[1,0]
	v_pk_add_f32 v[190:191], v[190:191], v[190:191] op_sel:[0,1] op_sel_hi:[1,0]
	v_exp_f32_e32 v199, v87
	v_add_f32_e32 v87, v106, v107
	v_mov_b32_e32 v105, v107
	v_pk_add_f32 v[106:107], v[228:229], v[214:215]
	v_pk_add_f32 v[110:111], v[206:207], v[204:205]
	v_sub_f32_e64 v191, -v107, v106
	v_sub_f32_e64 v227, -v111, v110
	v_mov_b32_e32 v193, v194
	v_pk_add_f32 v[190:191], v[226:227], v[190:191]
	v_pk_add_f32 v[238:239], v[180:181], v[178:179] neg_lo:[1,1] neg_hi:[1,1]
	v_pk_add_f32 v[104:105], v[104:105], v[192:193] neg_lo:[0,1] neg_hi:[0,1]
	v_mov_b32_e32 v95, v190
	v_mov_b32_e32 v103, v190
	v_pk_add_f32 v[238:239], v[238:239], v[238:239] op_sel_hi:[0,1]
	v_exp_f32_e32 v195, v87
	v_add_f32_e32 v87, v104, v105
	v_permlane32_swap_b32_e32 v95, v103
	v_exp_f32_e32 v194, v87
	v_add_f32_e32 v87, v156, v196
; __device__ __forceinline__ float exp2_(float x) { return __builtin_amdgcn_exp2f(x); }
; __device__ __forceinline__ float swap_partner(float x, int hh) { auto rr = __builtin_amdgcn_permlane32_swap(__float_as_uint(x), __float_as_uint(x), false, false); return __uint_as_float(hh ? rr[0] : rr[1]); }
; #define AT_RV(vf, mb) do { vf[0] = *(const LAS bf16x8*)(lds + vb + (mb) * 4096); vf[1] = *(const LAS bf16x8*)(lds + (vb ^ 32u) + (mb) * 4096); \
;                 vf[2] = *(const LAS bf16x8*)(lds + (vb ^ 64u) + (mb) * 4096); vf[3] = *(const LAS bf16x8*)(lds + (vb ^ 96u) + (mb) * 4096); } while (0)
; #define AT_PV(o, vf) do { __builtin_amdgcn_s_setprio(1); o = MFMA32(vf[0], p00, o); o = MFMA32(vf[1], p01, o); o = MFMA32(vf[2], p10, o); o = MFMA32(vf[3], p11, o); __builtin_amdgcn_s_setprio(0); } while (0)
; __device__ __forceinline__ void sb_sub(f32x16& s, float& carry, const int hh) {
;     ...
;     const float GAp = swap_partner(GA, hh), GBp = swap_partner(GB, hh);
;     float a = carry + (hh == 0 ? GBp : 0.f);
; #pragma unroll
;     for (int i = 15; i >= 8; --i) { const float wi = w[i]; s[i] = exp2_((s[i] + wi) + a); a += wi; }
;     a = carry + GB + GBp + (hh == 0 ? GAp : 0.f);
; #pragma unroll
;     for (int i = 7; i >= 0; --i) { const float wi = w[i]; s[i] = exp2_((s[i] + wi) + a); a += wi; }
;     carry += (GA + GB) + (GAp + GBp);
; template <int TYPE  >
; __device__ __forceinline__ void attn_item(const Params& P, const int b, const int h, const int qt, LAS unsigned char* lds) {
;     ...
;             const bf16x8 p00 = pack8(s0, 0), p01 = pack8(s0, 1), p10 = pack8(s1, 0), p11 = pack8(s1, 1);
;     ...
;             __builtin_amdgcn_sched_barrier(0);
;             AT_RV(vf1, 1); AT_PV(o0, vf0); __builtin_amdgcn_sched_barrier(0);
;             AT_RV(vf2, 2); AT_PV(o1, vf1); __builtin_amdgcn_sched_barrier(0);
	v_cndmask_b32_e64 v238, v95, v103, s[8:9]
	v_add_f32_e32 v87, v87, v244
	v_cndmask_b32_e64 v95, 0, v238, s[8:9]
	v_add_f32_e32 v103, v95, v87
	v_mov_b32_e32 v192, v161
	v_mov_b32_e32 v193, v177
	v_add_f32_e32 v87, v225, v103
	v_pk_add_f32 v[102:103], v[102:103], v[192:193] neg_lo:[0,1] neg_hi:[0,1]
	v_exp_f32_e32 v203, v87
	v_add_f32_e32 v87, v102, v103
	v_mov_b32_e32 v102, v101
	v_mov_b32_e32 v177, v161
	v_pk_add_f32 v[102:103], v[102:103], v[176:177] neg_lo:[0,1] neg_hi:[0,1]
	v_exp_f32_e32 v192, v87
	v_add_f32_e32 v87, v102, v103
	v_mov_b32_e32 v101, v103
	v_mov_b32_e32 v102, v160
	v_mov_b32_e32 v103, v176
	v_pk_add_f32 v[100:101], v[100:101], v[102:103] neg_lo:[0,1] neg_hi:[0,1]
	v_exp_f32_e32 v177, v87
	v_add_f32_e32 v87, v100, v101
	v_mov_b32_e32 v100, v99
	v_pk_mov_b32 v[102:103], v[158:159], v[160:161] op_sel:[1,0]
	v_exp_f32_e32 v176, v87
	v_pk_add_f32 v[100:101], v[100:101], v[102:103] neg_lo:[0,1] neg_hi:[0,1]
	v_mov_b32_e32 v246, v241
	v_add_f32_e32 v87, v100, v101
	v_mov_b32_e32 v99, v101
	v_mov_b32_e32 v100, v15
	v_mov_b32_e32 v101, v159
	v_pk_add_f32 v[98:99], v[98:99], v[100:101] neg_lo:[0,1] neg_hi:[0,1]
	v_exp_f32_e32 v102, v87
	v_add_f32_e32 v87, v98, v99
	v_mov_b32_e32 v98, v97
	v_mov_b32_e32 v159, v15
	v_pk_add_f32 v[98:99], v[98:99], v[158:159] neg_lo:[0,1] neg_hi:[0,1]
	v_exp_f32_e32 v100, v87
	v_add_f32_e32 v15, v98, v99
	v_exp_f32_e32 v98, v15
	v_mov_b32_e32 v97, v99
	v_mov_b32_e32 v15, v158
	v_pk_add_f32 v[14:15], v[96:97], v[14:15] neg_lo:[0,1] neg_hi:[0,1]
	v_pk_add_f32 v[96:97], v[238:239], v[244:245]
	v_add_f32_e32 v14, v14, v15
	v_exp_f32_e32 v99, v14
	v_pk_add_f32 v[14:15], v[190:191], v[196:197]
	v_mov_b32_e32 v101, v97
	v_mov_b32_e32 v87, v15
	v_mov_b32_e32 v95, v15
	s_nop 1
	v_permlane32_swap_b32_e32 v87, v95
	v_cndmask_b32_e64 v87, v87, v95, s[8:9]
	v_mov_b32_e32 v95, v97
	s_nop 1
	v_permlane32_swap_b32_e32 v95, v101
	v_cndmask_b32_e64 v101, v95, v101, s[8:9]
	v_pk_add_f32 v[14:15], v[14:15], v[96:97]
	v_add_f32_e32 v157, v87, v101
	v_cndmask_b32_e64 v95, 0, v101, s[8:9]
	v_pk_add_f32 v[14:15], v[156:157], v[14:15]
	v_mov_b32_e32 v247, v243
	v_add_f32_e32 v95, v14, v95
	v_add_f32_e32 v96, v252, v95
	v_pk_add_f32 v[94:95], v[94:95], v[246:247] neg_lo:[0,1] neg_hi:[0,1]
	v_mov_b32_e32 v243, v241
	v_add_f32_e32 v94, v94, v95
	v_exp_f32_e32 v103, v94
	v_mov_b32_e32 v94, v93
	v_pk_add_f32 v[94:95], v[94:95], v[242:243] neg_lo:[0,1] neg_hi:[0,1]
	v_mov_b32_e32 v248, v240
	v_add_f32_e32 v93, v94, v95
	v_mov_b32_e32 v249, v242
	v_exp_f32_e32 v94, v93
	v_mov_b32_e32 v93, v95
	v_pk_add_f32 v[92:93], v[92:93], v[248:249] neg_lo:[0,1] neg_hi:[0,1]
	v_pk_mov_b32 v[240:241], v[180:181], v[240:241] op_sel:[1,0]
	v_add_f32_e32 v92, v92, v93
	v_exp_f32_e32 v95, v92
	v_mov_b32_e32 v92, v91
	v_pk_add_f32 v[92:93], v[92:93], v[240:241] neg_lo:[0,1] neg_hi:[0,1]
	v_mov_b32_e32 v250, v179
	v_add_f32_e32 v91, v92, v93
	v_mov_b32_e32 v251, v181
	v_exp_f32_e32 v92, v91
	v_mov_b32_e32 v91, v93
	v_pk_add_f32 v[90:91], v[90:91], v[250:251] neg_lo:[0,1] neg_hi:[0,1]
	v_mov_b32_e32 v181, v179
	v_add_f32_e32 v90, v90, v91
	v_exp_f32_e32 v93, v90
	v_mov_b32_e32 v90, v89
	v_pk_add_f32 v[90:91], v[90:91], v[180:181] neg_lo:[0,1] neg_hi:[0,1]
	v_mov_b32_e32 v179, v180
	v_add_f32_e32 v89, v90, v91
	v_exp_f32_e32 v90, v89
	v_mov_b32_e32 v89, v91
	v_pk_add_f32 v[88:89], v[88:89], v[178:179] neg_lo:[0,1] neg_hi:[0,1]
	v_cndmask_b32_e64 v87, 0, v87, s[8:9]
	v_add_f32_e32 v88, v88, v89
	v_add_f32_e32 v89, v14, v97
	v_add_f32_e32 v89, v89, v101
	v_add_f32_e32 v87, v87, v89
	v_add_f32_e32 v89, v236, v87
	v_pk_add_f32 v[86:87], v[86:87], v[234:235] neg_lo:[0,1] neg_hi:[0,1]
	v_pk_mov_b32 v[104:105], v[230:231], v[234:235] op_sel:[1,0]
	v_add_f32_e32 v86, v86, v87
	v_exp_f32_e32 v91, v86
	v_mov_b32_e32 v86, v85
	v_pk_add_f32 v[86:87], v[86:87], v[104:105] neg_lo:[0,1] neg_hi:[0,1]
	v_pk_mov_b32 v[108:109], v[106:107], v[230:231] op_sel:[1,0]
	v_add_f32_e32 v85, v86, v87
	v_exp_f32_e32 v86, v85
	v_mov_b32_e32 v85, v87
	v_pk_add_f32 v[84:85], v[84:85], v[230:231] neg_lo:[0,1] neg_hi:[0,1]
	v_exp_f32_e32 v96, v96
	v_add_f32_e32 v87, v84, v85
	v_mov_b32_e32 v84, v83
	v_pk_add_f32 v[84:85], v[84:85], v[108:109] neg_lo:[0,1] neg_hi:[0,1]
	v_exp_f32_e32 v88, v88
	v_add_f32_e32 v83, v84, v85
	v_exp_f32_e32 v97, v83
	v_mov_b32_e32 v83, v85
	v_pk_add_f32 v[82:83], v[82:83], v[106:107] neg_lo:[0,1] neg_hi:[0,1]
	v_pk_mov_b32 v[84:85], v[110:111], v[106:107] op_sel:[1,0]
	v_add_f32_e32 v101, v82, v83
	v_mov_b32_e32 v82, v81
	v_pk_add_f32 v[82:83], v[82:83], v[84:85] neg_lo:[0,1] neg_hi:[0,1]
	v_exp_f32_e32 v89, v89
	v_add_f32_e32 v81, v82, v83
	v_exp_f32_e32 v82, v81
	v_mov_b32_e32 v81, v83
	v_pk_add_f32 v[80:81], v[80:81], v[110:111] neg_lo:[0,1] neg_hi:[0,1]
	v_exp_f32_e32 v83, v87
	v_add_f32_e32 v80, v80, v81
	v_exp_f32_e32 v80, v80
	v_exp_f32_e32 v81, v101
	v_add_f32_e32 v156, v14, v15
	v_cvt_pk_bf16_f32 v84, v88, v90
	v_cvt_pk_bf16_f32 v80, v80, v82
	v_cvt_pk_bf16_f32 v81, v81, v97
	v_cvt_pk_bf16_f32 v82, v83, v86
	v_cvt_pk_bf16_f32 v83, v91, v89
	v_cvt_pk_bf16_f32 v85, v93, v92
	v_cvt_pk_bf16_f32 v86, v95, v94
	v_cvt_pk_bf16_f32 v87, v103, v96
	v_cvt_pk_bf16_f32 v88, v99, v98
	v_cvt_pk_bf16_f32 v89, v100, v102
	v_cvt_pk_bf16_f32 v90, v176, v177
	v_cvt_pk_bf16_f32 v91, v192, v203
	v_cvt_pk_bf16_f32 v92, v194, v195
	v_cvt_pk_bf16_f32 v93, v199, v198
	v_cvt_pk_bf16_f32 v94, v200, v201
	v_cvt_pk_bf16_f32 v95, v202, v232
	ds_read_b128 v[96:99], v0 offset:20480
	ds_read_b128 v[100:103], v187 offset:4096
	ds_read_b128 v[104:107], v188 offset:4096
	ds_read_b128 v[108:111], v189 offset:4096
	s_waitcnt lgkmcnt(0)
; #define AT_RV(vf, mb) do { vf[0] = *(const LAS bf16x8*)(lds + vb + (mb) * 4096); vf[1] = *(const LAS bf16x8*)(lds + (vb ^ 32u) + (mb) * 4096); \
;                 vf[2] = *(const LAS bf16x8*)(lds + (vb ^ 64u) + (mb) * 4096); vf[3] = *(const LAS bf16x8*)(lds + (vb ^ 96u) + (mb) * 4096); } while (0)
; #define AT_PV(o, vf) do { __builtin_amdgcn_s_setprio(1); o = MFMA32(vf[0], p00, o); o = MFMA32(vf[1], p01, o); o = MFMA32(vf[2], p10, o); o = MFMA32(vf[3], p11, o); __builtin_amdgcn_s_setprio(0); } while (0)
; template <int TYPE  >
; __device__ __forceinline__ void attn_item(const Params& P, const int b, const int h, const int qt, LAS unsigned char* lds) {
;     ...
;             __builtin_amdgcn_sched_barrier(0);
;             AT_RV(vf1, 1); AT_PV(o0, vf0); __builtin_amdgcn_sched_barrier(0);
;             AT_RV(vf2, 2); AT_PV(o1, vf1); __builtin_amdgcn_sched_barrier(0);
;             AT_RV(vf3, 3); AT_PV(o2, vf2); __builtin_amdgcn_sched_barrier(0);
;             AT_PV(o3, vf3); __builtin_amdgcn_sched_barrier(0);
	v_mfma_f32_32x32x16_bf16 v[64:79], v[6:9], v[80:83], v[64:79]
	v_mfma_f32_32x32x16_bf16 v[64:79], v[2:5], v[84:87], v[64:79]
	v_mfma_f32_32x32x16_bf16 v[64:79], v[144:147], v[88:91], v[64:79]
	v_mfma_f32_32x32x16_bf16 v[64:79], v[10:13], v[92:95], v[64:79]
	ds_read_b128 v[2:5], v0 offset:24576
	ds_read_b128 v[6:9], v187 offset:8192
	ds_read_b128 v[10:13], v188 offset:8192
	ds_read_b128 v[144:147], v189 offset:8192
	v_mfma_f32_32x32x16_bf16 v[48:63], v[96:99], v[80:83], v[48:63]
	v_mfma_f32_32x32x16_bf16 v[48:63], v[100:103], v[84:87], v[48:63]
	v_mfma_f32_32x32x16_bf16 v[48:63], v[104:107], v[88:91], v[48:63]
	v_mfma_f32_32x32x16_bf16 v[48:63], v[108:111], v[92:95], v[48:63]
	ds_read_b128 v[96:99], v0 offset:28672
	ds_read_b128 v[100:103], v187 offset:12288
	ds_read_b128 v[104:107], v188 offset:12288
	ds_read_b128 v[108:111], v189 offset:12288
	s_waitcnt lgkmcnt(0)
	v_mfma_f32_32x32x16_bf16 v[32:47], v[2:5], v[80:83], v[32:47]
	v_mfma_f32_32x32x16_bf16 v[32:47], v[6:9], v[84:87], v[32:47]
	v_mfma_f32_32x32x16_bf16 v[32:47], v[10:13], v[88:91], v[32:47]
	v_mfma_f32_32x32x16_bf16 v[32:47], v[144:147], v[92:95], v[32:47]
	v_mfma_f32_32x32x16_bf16 v[16:31], v[96:99], v[80:83], v[16:31]
	v_mfma_f32_32x32x16_bf16 v[16:31], v[100:103], v[84:87], v[16:31]
	v_mfma_f32_32x32x16_bf16 v[16:31], v[104:107], v[88:91], v[16:31]
	v_mfma_f32_32x32x16_bf16 v[16:31], v[108:111], v[92:95], v[16:31]
	s_and_b64 vcc, exec, s[14:15]
	s_cbranch_vccnz .LBB0_1101

; __device__ __forceinline__ float max3_(float a, float b, float c) { float r; asm("v_max3_f32 %0, %1, %2, %3" : "=v"(r) : "v"(a), "v"(b), "v"(c)); return r; }
; __device__ __forceinline__ f32x2 pk_sub(f32x2 a, f32x2 b) { f32x2 r; asm("v_pk_add_f32 %0, %1, %2 neg_lo:[0,1] neg_hi:[0,1]" : "=v"(r) : "v"(a), "v"(b)); return r; }
; __device__ __forceinline__ float swap_max(float x) { auto rr = __builtin_amdgcn_permlane32_swap(__float_as_uint(x), __float_as_uint(x), false, false); return fmaxf(__uint_as_float(rr[0]), __uint_as_float(rr[1])); }
; template <int TYPE  >
; __device__ __forceinline__ void attn_item(const Params& P, const int b, const int h, const int qt, LAS unsigned char* lds) {
;     ...
;                 float mx = m_run;
; #pragma unroll
;                 for (int i = 0; i < 16; ++i) mx = max3_(mx, s0[i], s1[i]);
;                 asm volatile("s_nop 1" : "+v"(mx));
;                 const float mnew = swap_max(mx);
;                 const f32x2 mm = {mnew, mnew}; f32x2 rs2 = {0.f, 0.f};
; #pragma unroll
;                 for (int j = 0; j < 8; ++j) { const f32x2 x0 = pk_sub((f32x2){s0[2 * j], s0[2 * j + 1]}, mm), x1 = pk_sub((f32x2){s1[2 * j], s1[2 * j + 1]}, mm);
.LBB0_1128:
	s_waitcnt vmcnt(5)
	s_add_i32 s12, s10, 0
	s_barrier
	s_cmp_gt_i32 s11, s3
	s_cbranch_scc1 .LBB0_1132
	v_add_u32_e32 v0, s2, v230
	v_add_u32_e32 v214, 0, v0
	v_xad_u32 v215, v0, 32, 0
	v_xad_u32 v231, v0, 64, 0
	v_xor_b32_e32 v0, 0x60, v0
	v_add_u32_e32 v0, 0, v0
	ds_read_b128 v[146:149], v231
	ds_read_b128 v[150:153], v231 offset:12288
	ds_read_b128 v[154:157], v0
	ds_read_b128 v[158:161], v0 offset:12288
	ds_read_b128 v[66:69], v214
	ds_read_b128 v[192:195], v214 offset:128
	ds_read_b128 v[70:73], v214 offset:12288
	ds_read_b128 v[196:199], v214 offset:12416
	ds_read_b128 v[200:203], v215
	ds_read_b128 v[204:207], v215 offset:128
	ds_read_b128 v[236:239], v215 offset:12288
	ds_read_b128 v[240:243], v215 offset:12416
	s_waitcnt lgkmcnt(0)
	v_mfma_f32_32x32x16_bf16 v[82:97], v[66:69], v[142:145], 0
	v_mfma_f32_32x32x16_bf16 v[66:81], v[70:73], v[142:145], 0
	v_mfma_f32_32x32x16_bf16 v[82:97], v[200:203], v[138:141], v[82:97]
	v_mfma_f32_32x32x16_bf16 v[66:81], v[236:239], v[138:141], v[66:81]
	v_mfma_f32_32x32x16_bf16 v[82:97], v[146:149], v[134:137], v[82:97]
	v_mfma_f32_32x32x16_bf16 v[66:81], v[150:153], v[134:137], v[66:81]
	ds_read_b128 v[146:149], v231 offset:128
	ds_read_b128 v[150:153], v231 offset:12416
	ds_read_b128 v[200:203], v0 offset:128
	ds_read_b128 v[236:239], v0 offset:12416
	ds_read_b128 v[244:247], v214 offset:256
	ds_read_b128 v[248:251], v214 offset:12544
	v_mfma_f32_32x32x16_bf16 v[82:97], v[154:157], v[130:133], v[82:97]
	v_mfma_f32_32x32x16_bf16 v[66:81], v[158:161], v[130:133], v[66:81]
	v_mfma_f32_32x32x16_bf16 v[82:97], v[192:195], v[126:129], v[82:97]
	v_mfma_f32_32x32x16_bf16 v[66:81], v[196:199], v[126:129], v[66:81]
	v_mfma_f32_32x32x16_bf16 v[82:97], v[204:207], v[122:125], v[82:97]
	v_mfma_f32_32x32x16_bf16 v[66:81], v[240:243], v[122:125], v[66:81]
	ds_read_b128 v[154:157], v215 offset:256
	ds_read_b128 v[158:161], v215 offset:12544
	ds_read_b128 v[192:195], v231 offset:256
	ds_read_b128 v[196:199], v231 offset:12544
	ds_read_b128 v[204:207], v0 offset:256
	ds_read_b128 v[240:243], v0 offset:12544
	s_waitcnt lgkmcnt(0)
	v_mfma_f32_32x32x16_bf16 v[82:97], v[146:149], v[114:117], v[82:97]
	v_mfma_f32_32x32x16_bf16 v[66:81], v[150:153], v[114:117], v[66:81]
	v_mfma_f32_32x32x16_bf16 v[82:97], v[200:203], v[110:113], v[82:97]
	v_mfma_f32_32x32x16_bf16 v[66:81], v[236:239], v[110:113], v[66:81]
	v_mfma_f32_32x32x16_bf16 v[82:97], v[244:247], v[118:121], v[82:97]
	v_mfma_f32_32x32x16_bf16 v[66:81], v[248:251], v[118:121], v[66:81]
	v_mfma_f32_32x32x16_bf16 v[82:97], v[154:157], v[106:109], v[82:97]
	v_mfma_f32_32x32x16_bf16 v[66:81], v[158:161], v[106:109], v[66:81]
	v_mfma_f32_32x32x16_bf16 v[82:97], v[192:195], v[102:105], v[82:97]
	v_mfma_f32_32x32x16_bf16 v[66:81], v[196:199], v[102:105], v[66:81]
	v_mfma_f32_32x32x16_bf16 v[82:97], v[204:207], v[98:101], v[82:97]
	v_mfma_f32_32x32x16_bf16 v[66:81], v[240:243], v[98:101], v[66:81]
	v_add_u32_e32 v154, s2, v229
	v_add_u32_e32 v0, s2, v228
	v_xor_b32_e32 v155, 64, v154
	v_add_u32_e32 v0, 0, v0
	v_xor_b32_e32 v146, 32, v154
	v_add_u32_e32 v232, 0, v155
	v_xor_b32_e32 v154, 0x60, v154
	s_nop 7
	s_nop 7
	s_nop 3
	v_add_u32_e32 v231, 0, v146
	ds_read_b128 v[150:153], v0 offset:24576
	ds_read_b128 v[146:149], v231
	v_add_u32_e32 v233, 0, v154
	ds_read_b128 v[158:161], v232
	ds_read_b128 v[154:157], v233
	v_max3_f32 v192, v234, v82, v66
	s_nop 0
	v_max3_f32 v192, v192, v83, v67
	s_nop 0
	v_max3_f32 v192, v192, v84, v68
	s_nop 0
	v_max3_f32 v192, v192, v85, v69
	s_nop 0
	v_max3_f32 v192, v192, v86, v70
	s_nop 0
	v_max3_f32 v192, v192, v87, v71
	s_nop 0
	v_max3_f32 v192, v192, v88, v72
	s_nop 0
	v_max3_f32 v192, v192, v89, v73
	s_nop 0
	v_max3_f32 v192, v192, v90, v74
	s_nop 0
	v_max3_f32 v192, v192, v91, v75
	s_nop 0
	v_max3_f32 v192, v192, v92, v76
	s_nop 0
	v_max3_f32 v192, v192, v93, v77
	s_nop 0
	v_max3_f32 v192, v192, v94, v78
	s_nop 0
	v_max3_f32 v192, v192, v95, v79
	s_nop 0
	v_max3_f32 v192, v192, v96, v80
	s_nop 0
	v_max3_f32 v192, v192, v97, v81
	s_nop 0
	s_nop 1
	s_nop 0
	v_mov_b32_e32 v193, v192
	s_nop 1
	v_permlane32_swap_b32_e32 v192, v193
	v_max_f32_e32 v193, v193, v193
	v_max_f32_e32 v192, v192, v192
	v_max_f32_e32 v192, v192, v193
	v_cmp_gt_f32_e32 vcc, v192, v234
	v_mov_b32_e32 v193, v192
	v_pk_add_f32 v[206:207], v[82:83], v[192:193] neg_lo:[0,1] neg_hi:[0,1]
	v_pk_add_f32 v[204:205], v[66:67], v[192:193] neg_lo:[0,1] neg_hi:[0,1]
	v_pk_add_f32 v[202:203], v[84:85], v[192:193] neg_lo:[0,1] neg_hi:[0,1]
	v_pk_add_f32 v[200:201], v[68:69], v[192:193] neg_lo:[0,1] neg_hi:[0,1]
	v_pk_add_f32 v[198:199], v[86:87], v[192:193] neg_lo:[0,1] neg_hi:[0,1]
	v_pk_add_f32 v[196:197], v[70:71], v[192:193] neg_lo:[0,1] neg_hi:[0,1]
	v_pk_add_f32 v[194:195], v[88:89], v[192:193] neg_lo:[0,1] neg_hi:[0,1]
	v_pk_add_f32 v[88:89], v[72:73], v[192:193] neg_lo:[0,1] neg_hi:[0,1]
	v_pk_add_f32 v[86:87], v[90:91], v[192:193] neg_lo:[0,1] neg_hi:[0,1]
	v_pk_add_f32 v[84:85], v[74:75], v[192:193] neg_lo:[0,1] neg_hi:[0,1]
	v_pk_add_f32 v[82:83], v[92:93], v[192:193] neg_lo:[0,1] neg_hi:[0,1]
	v_pk_add_f32 v[74:75], v[76:77], v[192:193] neg_lo:[0,1] neg_hi:[0,1]
	v_pk_add_f32 v[72:73], v[94:95], v[192:193] neg_lo:[0,1] neg_hi:[0,1]
	v_pk_add_f32 v[70:71], v[78:79], v[192:193] neg_lo:[0,1] neg_hi:[0,1]
	v_pk_add_f32 v[68:69], v[96:97], v[192:193] neg_lo:[0,1] neg_hi:[0,1]
	v_pk_add_f32 v[66:67], v[80:81], v[192:193] neg_lo:[0,1] neg_hi:[0,1]
	s_cbranch_vccz .LBB0_1131
; __device__ __forceinline__ float exp2_(float x) { return __builtin_amdgcn_exp2f(x); }
; #define AT_RV(vf, mb) do { vf[0] = *(const LAS bf16x8*)(lds + vb + (mb) * 4096); vf[1] = *(const LAS bf16x8*)(lds + (vb ^ 32u) + (mb) * 4096); \
;                 vf[2] = *(const LAS bf16x8*)(lds + (vb ^ 64u) + (mb) * 4096); vf[3] = *(const LAS bf16x8*)(lds + (vb ^ 96u) + (mb) * 4096); } while (0)
; #define AT_PV(o, vf) do { __builtin_amdgcn_s_setprio(1); o = MFMA32(vf[0], p00, o); o = MFMA32(vf[1], p01, o); o = MFMA32(vf[2], p10, o); o = MFMA32(vf[3], p11, o); __builtin_amdgcn_s_setprio(0); } while (0)
; template <int TYPE  >
; __device__ __forceinline__ void attn_item(const Params& P, const int b, const int h, const int qt, LAS unsigned char* lds) {
;     ...
;                 if (__any(mnew > m_run)) {
;                     const float alpha = exp2_(m_run - mnew);
;                     l_run *= alpha; o0 *= alpha; o1 *= alpha; o2 *= alpha; o3 *= alpha;
;                 }
;                 l_run += rs; m_run = mnew;
;             }
;             const bf16x8 p00 = pack8(s0, 0), p01 = pack8(s0, 1), p10 = pack8(s1, 0), p11 = pack8(s1, 1);
;     ...
;             __builtin_amdgcn_sched_barrier(0);
;             AT_RV(vf1, 1); AT_PV(o0, vf0); __builtin_amdgcn_sched_barrier(0);
;             AT_RV(vf2, 2); AT_PV(o1, vf1); __builtin_amdgcn_sched_barrier(0);
;             AT_RV(vf3, 3); AT_PV(o2, vf2); __builtin_amdgcn_sched_barrier(0);
;             AT_PV(o3, vf3); __builtin_amdgcn_sched_barrier(0);
	v_sub_f32_e32 v76, v234, v192
	v_exp_f32_e32 v76, v76
	s_nop 0
	v_mul_f32_e32 v227, v227, v76
	v_pk_mul_f32 v[64:65], v[64:65], v[76:77] op_sel_hi:[1,0]
	v_pk_mul_f32 v[62:63], v[62:63], v[76:77] op_sel_hi:[1,0]
	v_pk_mul_f32 v[60:61], v[60:61], v[76:77] op_sel_hi:[1,0]
	v_pk_mul_f32 v[58:59], v[58:59], v[76:77] op_sel_hi:[1,0]
	v_pk_mul_f32 v[56:57], v[56:57], v[76:77] op_sel_hi:[1,0]
	v_pk_mul_f32 v[54:55], v[54:55], v[76:77] op_sel_hi:[1,0]
	v_pk_mul_f32 v[52:53], v[52:53], v[76:77] op_sel_hi:[1,0]
	v_pk_mul_f32 v[50:51], v[50:51], v[76:77] op_sel_hi:[1,0]
	v_pk_mul_f32 v[48:49], v[48:49], v[76:77] op_sel_hi:[1,0]
	v_pk_mul_f32 v[46:47], v[46:47], v[76:77] op_sel_hi:[1,0]
	v_pk_mul_f32 v[44:45], v[44:45], v[76:77] op_sel_hi:[1,0]
	v_pk_mul_f32 v[42:43], v[42:43], v[76:77] op_sel_hi:[1,0]
	v_pk_mul_f32 v[40:41], v[40:41], v[76:77] op_sel_hi:[1,0]
	v_pk_mul_f32 v[38:39], v[38:39], v[76:77] op_sel_hi:[1,0]
	v_pk_mul_f32 v[36:37], v[36:37], v[76:77] op_sel_hi:[1,0]
	v_pk_mul_f32 v[34:35], v[34:35], v[76:77] op_sel_hi:[1,0]
	v_pk_mul_f32 v[32:33], v[32:33], v[76:77] op_sel_hi:[1,0]
	v_pk_mul_f32 v[30:31], v[30:31], v[76:77] op_sel_hi:[1,0]
	v_pk_mul_f32 v[28:29], v[28:29], v[76:77] op_sel_hi:[1,0]
	v_pk_mul_f32 v[26:27], v[26:27], v[76:77] op_sel_hi:[1,0]
	v_pk_mul_f32 v[24:25], v[24:25], v[76:77] op_sel_hi:[1,0]
	v_pk_mul_f32 v[22:23], v[22:23], v[76:77] op_sel_hi:[1,0]
	v_pk_mul_f32 v[20:21], v[20:21], v[76:77] op_sel_hi:[1,0]
	v_pk_mul_f32 v[18:19], v[18:19], v[76:77] op_sel_hi:[1,0]
	v_pk_mul_f32 v[16:17], v[16:17], v[76:77] op_sel_hi:[1,0]
	v_pk_mul_f32 v[14:15], v[14:15], v[76:77] op_sel_hi:[1,0]
	v_pk_mul_f32 v[12:13], v[12:13], v[76:77] op_sel_hi:[1,0]
	v_pk_mul_f32 v[10:11], v[10:11], v[76:77] op_sel_hi:[1,0]
	v_pk_mul_f32 v[8:9], v[8:9], v[76:77] op_sel_hi:[1,0]
	v_pk_mul_f32 v[6:7], v[6:7], v[76:77] op_sel_hi:[1,0]
	v_pk_mul_f32 v[4:5], v[4:5], v[76:77] op_sel_hi:[1,0]
	v_pk_mul_f32 v[2:3], v[2:3], v[76:77] op_sel_hi:[1,0]
.LBB0_1131:
	v_exp_f32_e32 v76, v206
	v_exp_f32_e32 v77, v207
	v_exp_f32_e32 v78, v204
	v_exp_f32_e32 v79, v205
	v_exp_f32_e32 v80, v202
	v_exp_f32_e32 v81, v203
	v_exp_f32_e32 v90, v200
	v_exp_f32_e32 v91, v201
	v_exp_f32_e32 v96, v198
	v_exp_f32_e32 v97, v199
	v_exp_f32_e32 v196, v196
	v_exp_f32_e32 v197, v197
	v_exp_f32_e32 v194, v194
	v_exp_f32_e32 v195, v195
	v_exp_f32_e32 v88, v88
	v_exp_f32_e32 v89, v89
	v_pk_add_f32 v[92:93], v[76:77], v[78:79]
	v_pk_add_f32 v[94:95], v[80:81], v[90:91]
	v_pk_add_f32 v[92:93], v[92:93], 0 op_sel_hi:[1,0]
	v_exp_f32_e32 v86, v86
	v_pk_add_f32 v[92:93], v[92:93], v[94:95]
	v_pk_add_f32 v[94:95], v[96:97], v[196:197]
	v_exp_f32_e32 v87, v87
	v_exp_f32_e32 v84, v84
	v_exp_f32_e32 v85, v85
	v_pk_add_f32 v[92:93], v[92:93], v[94:95]
	v_pk_add_f32 v[94:95], v[194:195], v[88:89]
	v_exp_f32_e32 v82, v82
	v_exp_f32_e32 v83, v83
	v_exp_f32_e32 v198, v74
	v_exp_f32_e32 v199, v75
	v_pk_add_f32 v[74:75], v[92:93], v[94:95]
	v_exp_f32_e32 v72, v72
	v_exp_f32_e32 v73, v73
	v_exp_f32_e32 v94, v70
	v_exp_f32_e32 v95, v71
	v_exp_f32_e32 v200, v68
	v_exp_f32_e32 v201, v69
	v_exp_f32_e32 v202, v66
	v_exp_f32_e32 v203, v67
	v_pk_add_f32 v[92:93], v[86:87], v[84:85]
	v_pk_add_f32 v[68:69], v[72:73], v[94:95]
	v_pk_add_f32 v[74:75], v[74:75], v[92:93]
	v_pk_add_f32 v[92:93], v[82:83], v[198:199]
	v_cvt_pk_bf16_f32 v70, v86, v87
	v_pk_add_f32 v[66:67], v[74:75], v[92:93]
	v_cvt_pk_bf16_f32 v71, v82, v83
	v_pk_add_f32 v[66:67], v[66:67], v[68:69]
	v_pk_add_f32 v[68:69], v[200:201], v[202:203]
	v_cvt_pk_bf16_f32 v72, v72, v73
	v_pk_add_f32 v[66:67], v[66:67], v[68:69]
	v_cvt_pk_bf16_f32 v68, v96, v97
	v_add_f32_e32 v66, v66, v67
	v_add_f32_e32 v227, v66, v227
	v_cvt_pk_bf16_f32 v66, v76, v77
	v_cvt_pk_bf16_f32 v67, v80, v81
	v_cvt_pk_bf16_f32 v69, v194, v195
	v_cvt_pk_bf16_f32 v73, v200, v201
	v_cvt_pk_bf16_f32 v74, v78, v79
	v_cvt_pk_bf16_f32 v75, v90, v91
	v_cvt_pk_bf16_f32 v76, v196, v197
	v_cvt_pk_bf16_f32 v77, v88, v89
	v_cvt_pk_bf16_f32 v78, v84, v85
	v_cvt_pk_bf16_f32 v79, v198, v199
	v_cvt_pk_bf16_f32 v80, v94, v95
	v_cvt_pk_bf16_f32 v81, v202, v203
	ds_read_b128 v[82:85], v0 offset:28672
	ds_read_b128 v[86:89], v231 offset:4096
	ds_read_b128 v[90:93], v232 offset:4096
	ds_read_b128 v[94:97], v233 offset:4096
	s_waitcnt lgkmcnt(0)
	v_mfma_f32_32x32x16_bf16 v[50:65], v[150:153], v[66:69], v[50:65]
	v_mfma_f32_32x32x16_bf16 v[50:65], v[146:149], v[70:73], v[50:65]
	v_mfma_f32_32x32x16_bf16 v[50:65], v[158:161], v[74:77], v[50:65]
	v_mfma_f32_32x32x16_bf16 v[50:65], v[154:157], v[78:81], v[50:65]
	s_add_i32 m0, s12, s4
	s_nop 0
	global_load_lds_dwordx4 v[190:191], off
	s_add_i32 m0, s12, s5
	s_nop 0
	global_load_lds_dwordx4 v[188:189], off
	ds_read_b128 v[146:149], v0 offset:32768
	ds_read_b128 v[150:153], v231 offset:8192
	ds_read_b128 v[154:157], v232 offset:8192
	ds_read_b128 v[158:161], v233 offset:8192
	v_mfma_f32_32x32x16_bf16 v[34:49], v[82:85], v[66:69], v[34:49]
	v_mfma_f32_32x32x16_bf16 v[34:49], v[86:89], v[70:73], v[34:49]
	v_mfma_f32_32x32x16_bf16 v[34:49], v[90:93], v[74:77], v[34:49]
	v_mfma_f32_32x32x16_bf16 v[34:49], v[94:97], v[78:81], v[34:49]
	s_add_i32 m0, s12, s7
	s_add_i32 s12, s12, s8
	global_load_lds_dwordx4 v[186:187], off
	s_add_i32 m0, s12, 0x6000
	s_nop 0
	global_load_lds_dwordx4 v[184:185], off
	ds_read_b128 v[82:85], v0 offset:36864
	ds_read_b128 v[86:89], v231 offset:12288
	ds_read_b128 v[90:93], v232 offset:12288
	ds_read_b128 v[94:97], v233 offset:12288
	s_waitcnt lgkmcnt(0)
	v_mfma_f32_32x32x16_bf16 v[18:33], v[146:149], v[66:69], v[18:33]
	v_mfma_f32_32x32x16_bf16 v[18:33], v[150:153], v[70:73], v[18:33]
	v_mfma_f32_32x32x16_bf16 v[18:33], v[154:157], v[74:77], v[18:33]
	v_mfma_f32_32x32x16_bf16 v[18:33], v[158:161], v[78:81], v[18:33]
	s_add_i32 m0, s12, 0x6400
	s_nop 0
	global_load_lds_dwordx4 v[182:183], off
	v_mfma_f32_32x32x16_bf16 v[2:17], v[82:85], v[66:69], v[2:17]
	v_mfma_f32_32x32x16_bf16 v[2:17], v[86:89], v[70:73], v[2:17]
	v_mfma_f32_32x32x16_bf16 v[2:17], v[90:93], v[74:77], v[2:17]
	v_mfma_f32_32x32x16_bf16 v[2:17], v[94:97], v[78:81], v[2:17]
	s_branch .LBB0_1133

; __device__ __forceinline__ float max3_(float a, float b, float c) { float r; asm("v_max3_f32 %0, %1, %2, %3" : "=v"(r) : "v"(a), "v"(b), "v"(c)); return r; }
; __device__ __forceinline__ f32x2 pk_sub(f32x2 a, f32x2 b) { f32x2 r; asm("v_pk_add_f32 %0, %1, %2 neg_lo:[0,1] neg_hi:[0,1]" : "=v"(r) : "v"(a), "v"(b)); return r; }
; __device__ __forceinline__ float swap_max(float x) { auto rr = __builtin_amdgcn_permlane32_swap(__float_as_uint(x), __float_as_uint(x), false, false); return fmaxf(__uint_as_float(rr[0]), __uint_as_float(rr[1])); }
; template <int TYPE  >
; __device__ __forceinline__ void attn_item(const Params& P, const int b, const int h, const int qt, LAS unsigned char* lds) {
;     ...
;                 float mx = m_run;
; #pragma unroll
;                 for (int i = 0; i < 16; ++i) mx = max3_(mx, s0[i], s1[i]);
;                 asm volatile("s_nop 1" : "+v"(mx));
;                 const float mnew = swap_max(mx);
;                 const f32x2 mm = {mnew, mnew}; f32x2 rs2 = {0.f, 0.f};
; #pragma unroll
;                 for (int j = 0; j < 8; ++j) { const f32x2 x0 = pk_sub((f32x2){s0[2 * j], s0[2 * j + 1]}, mm), x1 = pk_sub((f32x2){s1[2 * j], s1[2 * j + 1]}, mm);
.LBB0_1136:
	s_waitcnt vmcnt(5)
	s_barrier
	s_cmp_lt_i32 s9, 2
	s_cbranch_scc1 .LBB0_1140
	v_add_u32_e32 v0, s2, v230
	v_add_u32_e32 v193, 0, v0
	v_xad_u32 v206, v0, 32, 0
	v_xad_u32 v207, v0, 64, 0
	v_xor_b32_e32 v0, 0x60, v0
	v_add_u32_e32 v0, 0, v0
	ds_read_b128 v[146:149], v207
	ds_read_b128 v[150:153], v207 offset:12288
	ds_read_b128 v[154:157], v0
	ds_read_b128 v[158:161], v0 offset:12288
	ds_read_b128 v[66:69], v193
	ds_read_b128 v[176:179], v193 offset:128
	ds_read_b128 v[70:73], v193 offset:12288
	ds_read_b128 v[180:183], v193 offset:12416
	ds_read_b128 v[184:187], v206
	ds_read_b128 v[188:191], v206 offset:128
	ds_read_b128 v[194:197], v206 offset:12288
	ds_read_b128 v[198:201], v206 offset:12416
	s_waitcnt lgkmcnt(0)
	v_mfma_f32_32x32x16_bf16 v[82:97], v[66:69], v[142:145], 0
	v_mfma_f32_32x32x16_bf16 v[66:81], v[70:73], v[142:145], 0
	v_mfma_f32_32x32x16_bf16 v[82:97], v[184:187], v[138:141], v[82:97]
	v_mfma_f32_32x32x16_bf16 v[66:81], v[194:197], v[138:141], v[66:81]
	v_mfma_f32_32x32x16_bf16 v[82:97], v[146:149], v[134:137], v[82:97]
	v_mfma_f32_32x32x16_bf16 v[66:81], v[150:153], v[134:137], v[66:81]
	ds_read_b128 v[146:149], v207 offset:128
	ds_read_b128 v[150:153], v207 offset:12416
	ds_read_b128 v[184:187], v0 offset:128
	ds_read_b128 v[194:197], v0 offset:12416
	ds_read_b128 v[202:205], v193 offset:256
	ds_read_b128 v[232:235], v193 offset:12544
	v_mfma_f32_32x32x16_bf16 v[82:97], v[154:157], v[130:133], v[82:97]
	v_mfma_f32_32x32x16_bf16 v[66:81], v[158:161], v[130:133], v[66:81]
	v_mfma_f32_32x32x16_bf16 v[82:97], v[176:179], v[126:129], v[82:97]
	v_mfma_f32_32x32x16_bf16 v[66:81], v[180:183], v[126:129], v[66:81]
	v_mfma_f32_32x32x16_bf16 v[82:97], v[188:191], v[122:125], v[82:97]
	v_mfma_f32_32x32x16_bf16 v[66:81], v[198:201], v[122:125], v[66:81]
	ds_read_b128 v[154:157], v206 offset:256
	ds_read_b128 v[158:161], v206 offset:12544
	ds_read_b128 v[176:179], v207 offset:256
	ds_read_b128 v[180:183], v207 offset:12544
	ds_read_b128 v[188:191], v0 offset:256
	ds_read_b128 v[198:201], v0 offset:12544
	s_waitcnt lgkmcnt(0)
	v_mfma_f32_32x32x16_bf16 v[82:97], v[146:149], v[114:117], v[82:97]
	v_mfma_f32_32x32x16_bf16 v[66:81], v[150:153], v[114:117], v[66:81]
	v_mfma_f32_32x32x16_bf16 v[82:97], v[184:187], v[110:113], v[82:97]
	v_mfma_f32_32x32x16_bf16 v[66:81], v[194:197], v[110:113], v[66:81]
	v_mfma_f32_32x32x16_bf16 v[82:97], v[202:205], v[118:121], v[82:97]
	v_mfma_f32_32x32x16_bf16 v[66:81], v[232:235], v[118:121], v[66:81]
	v_mfma_f32_32x32x16_bf16 v[82:97], v[154:157], v[106:109], v[82:97]
	v_mfma_f32_32x32x16_bf16 v[66:81], v[158:161], v[106:109], v[66:81]
	v_mfma_f32_32x32x16_bf16 v[82:97], v[176:179], v[102:105], v[82:97]
	v_mfma_f32_32x32x16_bf16 v[66:81], v[180:183], v[102:105], v[66:81]
	v_mfma_f32_32x32x16_bf16 v[82:97], v[188:191], v[98:101], v[82:97]
	v_mfma_f32_32x32x16_bf16 v[66:81], v[198:201], v[98:101], v[66:81]
	v_add_u32_e32 v154, s2, v229
	v_add_u32_e32 v0, s2, v228
	v_xor_b32_e32 v155, 64, v154
	v_add_u32_e32 v0, 0, v0
	v_xor_b32_e32 v146, 32, v154
	v_add_u32_e32 v194, 0, v155
	v_xor_b32_e32 v154, 0x60, v154
	s_nop 7
	s_nop 7
	s_nop 3
	v_add_u32_e32 v193, 0, v146
	ds_read_b128 v[150:153], v0 offset:24576
	ds_read_b128 v[146:149], v193
	v_add_u32_e32 v195, 0, v154
	ds_read_b128 v[158:161], v194
	ds_read_b128 v[154:157], v195
	v_max3_f32 v176, v192, v82, v66
	s_nop 0
	v_max3_f32 v176, v176, v83, v67
	s_nop 0
	v_max3_f32 v176, v176, v84, v68
	s_nop 0
	v_max3_f32 v176, v176, v85, v69
	s_nop 0
	v_max3_f32 v176, v176, v86, v70
	s_nop 0
	v_max3_f32 v176, v176, v87, v71
	s_nop 0
	v_max3_f32 v176, v176, v88, v72
	s_nop 0
	v_max3_f32 v176, v176, v89, v73
	s_nop 0
	v_max3_f32 v176, v176, v90, v74
	s_nop 0
	v_max3_f32 v176, v176, v91, v75
	s_nop 0
	v_max3_f32 v176, v176, v92, v76
	s_nop 0
	v_max3_f32 v176, v176, v93, v77
	s_nop 0
	v_max3_f32 v176, v176, v94, v78
	s_nop 0
	v_max3_f32 v176, v176, v95, v79
	s_nop 0
	v_max3_f32 v176, v176, v96, v80
	s_nop 0
	v_max3_f32 v176, v176, v97, v81
	s_nop 0
	s_nop 1
	s_nop 0
	v_mov_b32_e32 v177, v176
	s_nop 1
	v_permlane32_swap_b32_e32 v176, v177
	v_max_f32_e32 v177, v177, v177
	v_max_f32_e32 v176, v176, v176
	v_max_f32_e32 v176, v176, v177
	v_cmp_gt_f32_e32 vcc, v176, v192
	v_mov_b32_e32 v177, v176
	v_pk_add_f32 v[190:191], v[82:83], v[176:177] neg_lo:[0,1] neg_hi:[0,1]
	v_pk_add_f32 v[188:189], v[66:67], v[176:177] neg_lo:[0,1] neg_hi:[0,1]
	v_pk_add_f32 v[186:187], v[84:85], v[176:177] neg_lo:[0,1] neg_hi:[0,1]
	v_pk_add_f32 v[184:185], v[68:69], v[176:177] neg_lo:[0,1] neg_hi:[0,1]
	v_pk_add_f32 v[182:183], v[86:87], v[176:177] neg_lo:[0,1] neg_hi:[0,1]
	v_pk_add_f32 v[180:181], v[70:71], v[176:177] neg_lo:[0,1] neg_hi:[0,1]
	v_pk_add_f32 v[178:179], v[88:89], v[176:177] neg_lo:[0,1] neg_hi:[0,1]
	v_pk_add_f32 v[88:89], v[72:73], v[176:177] neg_lo:[0,1] neg_hi:[0,1]
	v_pk_add_f32 v[86:87], v[90:91], v[176:177] neg_lo:[0,1] neg_hi:[0,1]
	v_pk_add_f32 v[84:85], v[74:75], v[176:177] neg_lo:[0,1] neg_hi:[0,1]
	v_pk_add_f32 v[82:83], v[92:93], v[176:177] neg_lo:[0,1] neg_hi:[0,1]
	v_pk_add_f32 v[74:75], v[76:77], v[176:177] neg_lo:[0,1] neg_hi:[0,1]
	v_pk_add_f32 v[72:73], v[94:95], v[176:177] neg_lo:[0,1] neg_hi:[0,1]
	v_pk_add_f32 v[70:71], v[78:79], v[176:177] neg_lo:[0,1] neg_hi:[0,1]
	v_pk_add_f32 v[68:69], v[96:97], v[176:177] neg_lo:[0,1] neg_hi:[0,1]
	v_pk_add_f32 v[66:67], v[80:81], v[176:177] neg_lo:[0,1] neg_hi:[0,1]
	s_cbranch_vccz .LBB0_1139
; __device__ __forceinline__ float exp2_(float x) { return __builtin_amdgcn_exp2f(x); }
; #define AT_RV(vf, mb) do { vf[0] = *(const LAS bf16x8*)(lds + vb + (mb) * 4096); vf[1] = *(const LAS bf16x8*)(lds + (vb ^ 32u) + (mb) * 4096); \
;                 vf[2] = *(const LAS bf16x8*)(lds + (vb ^ 64u) + (mb) * 4096); vf[3] = *(const LAS bf16x8*)(lds + (vb ^ 96u) + (mb) * 4096); } while (0)
; #define AT_PV(o, vf) do { __builtin_amdgcn_s_setprio(1); o = MFMA32(vf[0], p00, o); o = MFMA32(vf[1], p01, o); o = MFMA32(vf[2], p10, o); o = MFMA32(vf[3], p11, o); __builtin_amdgcn_s_setprio(0); } while (0)
; template <int TYPE  >
; __device__ __forceinline__ void attn_item(const Params& P, const int b, const int h, const int qt, LAS unsigned char* lds) {
;     ...
;                 if (__any(mnew > m_run)) {
;                     const float alpha = exp2_(m_run - mnew);
;                     l_run *= alpha; o0 *= alpha; o1 *= alpha; o2 *= alpha; o3 *= alpha;
;                 }
;                 l_run += rs; m_run = mnew;
;             }
;             const bf16x8 p00 = pack8(s0, 0), p01 = pack8(s0, 1), p10 = pack8(s1, 0), p11 = pack8(s1, 1);
;     ...
;             __builtin_amdgcn_sched_barrier(0);
;             AT_RV(vf1, 1); AT_PV(o0, vf0); __builtin_amdgcn_sched_barrier(0);
;             AT_RV(vf2, 2); AT_PV(o1, vf1); __builtin_amdgcn_sched_barrier(0);
;             AT_RV(vf3, 3); AT_PV(o2, vf2); __builtin_amdgcn_sched_barrier(0);
;             AT_PV(o3, vf3); __builtin_amdgcn_sched_barrier(0);
	v_sub_f32_e32 v76, v192, v176
	v_exp_f32_e32 v76, v76
	s_nop 0
	v_mul_f32_e32 v227, v227, v76
	v_pk_mul_f32 v[64:65], v[64:65], v[76:77] op_sel_hi:[1,0]
	v_pk_mul_f32 v[62:63], v[62:63], v[76:77] op_sel_hi:[1,0]
	v_pk_mul_f32 v[60:61], v[60:61], v[76:77] op_sel_hi:[1,0]
	v_pk_mul_f32 v[58:59], v[58:59], v[76:77] op_sel_hi:[1,0]
	v_pk_mul_f32 v[56:57], v[56:57], v[76:77] op_sel_hi:[1,0]
	v_pk_mul_f32 v[54:55], v[54:55], v[76:77] op_sel_hi:[1,0]
	v_pk_mul_f32 v[52:53], v[52:53], v[76:77] op_sel_hi:[1,0]
	v_pk_mul_f32 v[50:51], v[50:51], v[76:77] op_sel_hi:[1,0]
	v_pk_mul_f32 v[48:49], v[48:49], v[76:77] op_sel_hi:[1,0]
	v_pk_mul_f32 v[46:47], v[46:47], v[76:77] op_sel_hi:[1,0]
	v_pk_mul_f32 v[44:45], v[44:45], v[76:77] op_sel_hi:[1,0]
	v_pk_mul_f32 v[42:43], v[42:43], v[76:77] op_sel_hi:[1,0]
	v_pk_mul_f32 v[40:41], v[40:41], v[76:77] op_sel_hi:[1,0]
	v_pk_mul_f32 v[38:39], v[38:39], v[76:77] op_sel_hi:[1,0]
	v_pk_mul_f32 v[36:37], v[36:37], v[76:77] op_sel_hi:[1,0]
	v_pk_mul_f32 v[34:35], v[34:35], v[76:77] op_sel_hi:[1,0]
	v_pk_mul_f32 v[32:33], v[32:33], v[76:77] op_sel_hi:[1,0]
	v_pk_mul_f32 v[30:31], v[30:31], v[76:77] op_sel_hi:[1,0]
	v_pk_mul_f32 v[28:29], v[28:29], v[76:77] op_sel_hi:[1,0]
	v_pk_mul_f32 v[26:27], v[26:27], v[76:77] op_sel_hi:[1,0]
	v_pk_mul_f32 v[24:25], v[24:25], v[76:77] op_sel_hi:[1,0]
	v_pk_mul_f32 v[22:23], v[22:23], v[76:77] op_sel_hi:[1,0]
	v_pk_mul_f32 v[20:21], v[20:21], v[76:77] op_sel_hi:[1,0]
	v_pk_mul_f32 v[18:19], v[18:19], v[76:77] op_sel_hi:[1,0]
	v_pk_mul_f32 v[16:17], v[16:17], v[76:77] op_sel_hi:[1,0]
	v_pk_mul_f32 v[14:15], v[14:15], v[76:77] op_sel_hi:[1,0]
	v_pk_mul_f32 v[12:13], v[12:13], v[76:77] op_sel_hi:[1,0]
	v_pk_mul_f32 v[10:11], v[10:11], v[76:77] op_sel_hi:[1,0]
	v_pk_mul_f32 v[8:9], v[8:9], v[76:77] op_sel_hi:[1,0]
	v_pk_mul_f32 v[6:7], v[6:7], v[76:77] op_sel_hi:[1,0]
	v_pk_mul_f32 v[4:5], v[4:5], v[76:77] op_sel_hi:[1,0]
	v_pk_mul_f32 v[2:3], v[2:3], v[76:77] op_sel_hi:[1,0]
.LBB0_1139:
	v_exp_f32_e32 v76, v190
	v_exp_f32_e32 v77, v191
	v_exp_f32_e32 v78, v188
	v_exp_f32_e32 v79, v189
	v_exp_f32_e32 v80, v186
	v_exp_f32_e32 v81, v187
	v_exp_f32_e32 v90, v184
	v_exp_f32_e32 v91, v185
	v_exp_f32_e32 v96, v182
	v_exp_f32_e32 v97, v183
	v_exp_f32_e32 v180, v180
	v_exp_f32_e32 v181, v181
	v_exp_f32_e32 v178, v178
	v_exp_f32_e32 v179, v179
	v_exp_f32_e32 v88, v88
	v_exp_f32_e32 v89, v89
	v_pk_add_f32 v[92:93], v[76:77], v[78:79]
	v_pk_add_f32 v[94:95], v[80:81], v[90:91]
	v_pk_add_f32 v[92:93], v[92:93], 0 op_sel_hi:[1,0]
	v_exp_f32_e32 v86, v86
	v_pk_add_f32 v[92:93], v[92:93], v[94:95]
	v_pk_add_f32 v[94:95], v[96:97], v[180:181]
	v_exp_f32_e32 v87, v87
	v_exp_f32_e32 v84, v84
	v_exp_f32_e32 v85, v85
	v_pk_add_f32 v[92:93], v[92:93], v[94:95]
	v_pk_add_f32 v[94:95], v[178:179], v[88:89]
	v_exp_f32_e32 v82, v82
	v_exp_f32_e32 v83, v83
	v_exp_f32_e32 v182, v74
	v_exp_f32_e32 v183, v75
	v_pk_add_f32 v[74:75], v[92:93], v[94:95]
	v_exp_f32_e32 v72, v72
	v_exp_f32_e32 v73, v73
	v_exp_f32_e32 v94, v70
	v_exp_f32_e32 v95, v71
	v_exp_f32_e32 v184, v68
	v_exp_f32_e32 v185, v69
	v_exp_f32_e32 v186, v66
	v_exp_f32_e32 v187, v67
	v_pk_add_f32 v[92:93], v[86:87], v[84:85]
	v_pk_add_f32 v[68:69], v[72:73], v[94:95]
	v_pk_add_f32 v[74:75], v[74:75], v[92:93]
	v_pk_add_f32 v[92:93], v[82:83], v[182:183]
	v_cvt_pk_bf16_f32 v70, v86, v87
	v_pk_add_f32 v[66:67], v[74:75], v[92:93]
	v_cvt_pk_bf16_f32 v71, v82, v83
	v_pk_add_f32 v[66:67], v[66:67], v[68:69]
	v_pk_add_f32 v[68:69], v[184:185], v[186:187]
	v_cvt_pk_bf16_f32 v72, v72, v73
	v_pk_add_f32 v[66:67], v[66:67], v[68:69]
	v_cvt_pk_bf16_f32 v68, v96, v97
	v_add_f32_e32 v66, v66, v67
	v_add_f32_e32 v227, v66, v227
	v_cvt_pk_bf16_f32 v66, v76, v77
	v_cvt_pk_bf16_f32 v67, v80, v81
	v_cvt_pk_bf16_f32 v69, v178, v179
	v_cvt_pk_bf16_f32 v73, v184, v185
	v_cvt_pk_bf16_f32 v74, v78, v79
	v_cvt_pk_bf16_f32 v75, v90, v91
	v_cvt_pk_bf16_f32 v76, v180, v181
	v_cvt_pk_bf16_f32 v77, v88, v89
	v_cvt_pk_bf16_f32 v78, v84, v85
	v_cvt_pk_bf16_f32 v79, v182, v183
	v_cvt_pk_bf16_f32 v80, v94, v95
	v_cvt_pk_bf16_f32 v81, v186, v187
	ds_read_b128 v[82:85], v0 offset:28672
	ds_read_b128 v[86:89], v193 offset:4096
	ds_read_b128 v[90:93], v194 offset:4096
	ds_read_b128 v[94:97], v195 offset:4096
	s_waitcnt lgkmcnt(0)
	v_mfma_f32_32x32x16_bf16 v[50:65], v[150:153], v[66:69], v[50:65]
	v_mfma_f32_32x32x16_bf16 v[50:65], v[146:149], v[70:73], v[50:65]
	v_mfma_f32_32x32x16_bf16 v[50:65], v[158:161], v[74:77], v[50:65]
	v_mfma_f32_32x32x16_bf16 v[50:65], v[154:157], v[78:81], v[50:65]
	ds_read_b128 v[146:149], v0 offset:32768
	ds_read_b128 v[150:153], v193 offset:8192
	ds_read_b128 v[154:157], v194 offset:8192
	ds_read_b128 v[158:161], v195 offset:8192
	v_mfma_f32_32x32x16_bf16 v[34:49], v[82:85], v[66:69], v[34:49]
	v_mfma_f32_32x32x16_bf16 v[34:49], v[86:89], v[70:73], v[34:49]
	v_mfma_f32_32x32x16_bf16 v[34:49], v[90:93], v[74:77], v[34:49]
	v_mfma_f32_32x32x16_bf16 v[34:49], v[94:97], v[78:81], v[34:49]
	ds_read_b128 v[82:85], v0 offset:36864
	ds_read_b128 v[86:89], v193 offset:12288
	ds_read_b128 v[90:93], v194 offset:12288
	ds_read_b128 v[94:97], v195 offset:12288
	s_waitcnt lgkmcnt(0)
	v_mfma_f32_32x32x16_bf16 v[18:33], v[146:149], v[66:69], v[18:33]
	v_mfma_f32_32x32x16_bf16 v[18:33], v[150:153], v[70:73], v[18:33]
	v_mfma_f32_32x32x16_bf16 v[18:33], v[154:157], v[74:77], v[18:33]
	v_mfma_f32_32x32x16_bf16 v[18:33], v[158:161], v[78:81], v[18:33]
	v_mfma_f32_32x32x16_bf16 v[2:17], v[82:85], v[66:69], v[2:17]
	v_mfma_f32_32x32x16_bf16 v[2:17], v[86:89], v[70:73], v[2:17]
	v_mfma_f32_32x32x16_bf16 v[2:17], v[90:93], v[74:77], v[2:17]
	v_mfma_f32_32x32x16_bf16 v[2:17], v[94:97], v[78:81], v[2:17]
	s_branch .LBB0_1141

; __device__ __forceinline__ float max3_(float a, float b, float c) { float r; asm("v_max3_f32 %0, %1, %2, %3" : "=v"(r) : "v"(a), "v"(b), "v"(c)); return r; }
; __device__ __forceinline__ f32x2 pk_sub(f32x2 a, f32x2 b) { f32x2 r; asm("v_pk_add_f32 %0, %1, %2 neg_lo:[0,1] neg_hi:[0,1]" : "=v"(r) : "v"(a), "v"(b)); return r; }
; __device__ __forceinline__ float swap_max(float x) { auto rr = __builtin_amdgcn_permlane32_swap(__float_as_uint(x), __float_as_uint(x), false, false); return fmaxf(__uint_as_float(rr[0]), __uint_as_float(rr[1])); }
; template <int TYPE  >
; __device__ __forceinline__ void attn_item(const Params& P, const int b, const int h, const int qt, LAS unsigned char* lds) {
;     ...
;                 float mx = m_run;
; #pragma unroll
;                 for (int i = 0; i < 16; ++i) mx = max3_(mx, s0[i], s1[i]);
;                 asm volatile("s_nop 1" : "+v"(mx));
;                 const float mnew = swap_max(mx);
;                 const f32x2 mm = {mnew, mnew}; f32x2 rs2 = {0.f, 0.f};
; #pragma unroll
;                 for (int j = 0; j < 8; ++j) { const f32x2 x0 = pk_sub((f32x2){s0[2 * j], s0[2 * j + 1]}, mm), x1 = pk_sub((f32x2){s1[2 * j], s1[2 * j + 1]}, mm);
.LBB0_1141:
	s_waitcnt vmcnt(0)
	s_barrier
	s_cmp_ge_i32 s37, s3
	s_cbranch_scc1 .LBB0_1145
	s_add_i32 s3, s2, 0xa000
	s_cmp_lg_u32 s2, 0x14000
	s_cselect_b32 s2, s3, 0
	v_add_u32_e32 v0, s2, v230
	v_add_u32_e32 v177, 0, v0
	v_xad_u32 v202, v0, 32, 0
	v_xad_u32 v203, v0, 64, 0
	v_xor_b32_e32 v0, 0x60, v0
	v_add_u32_e32 v0, 0, v0
	ds_read_b128 v[146:149], v203
	ds_read_b128 v[150:153], v203 offset:12288
	ds_read_b128 v[154:157], v0
	ds_read_b128 v[158:161], v0 offset:12288
	ds_read_b128 v[66:69], v177
	ds_read_b128 v[178:181], v177 offset:128
	ds_read_b128 v[70:73], v177 offset:12288
	ds_read_b128 v[182:185], v177 offset:12416
	ds_read_b128 v[186:189], v202
	ds_read_b128 v[190:193], v202 offset:128
	ds_read_b128 v[194:197], v202 offset:12288
	ds_read_b128 v[198:201], v202 offset:12416
	s_waitcnt lgkmcnt(0)
	v_mfma_f32_32x32x16_bf16 v[82:97], v[66:69], v[142:145], 0
	v_mfma_f32_32x32x16_bf16 v[66:81], v[70:73], v[142:145], 0
	v_mfma_f32_32x32x16_bf16 v[82:97], v[186:189], v[138:141], v[82:97]
	v_mfma_f32_32x32x16_bf16 v[66:81], v[194:197], v[138:141], v[66:81]
	v_mfma_f32_32x32x16_bf16 v[82:97], v[146:149], v[134:137], v[82:97]
	v_mfma_f32_32x32x16_bf16 v[66:81], v[150:153], v[134:137], v[66:81]
	ds_read_b128 v[134:137], v203 offset:128
	ds_read_b128 v[138:141], v203 offset:12416
	ds_read_b128 v[142:145], v0 offset:128
	ds_read_b128 v[146:149], v0 offset:12416
	ds_read_b128 v[150:153], v177 offset:256
	ds_read_b128 v[186:189], v177 offset:12544
	v_mfma_f32_32x32x16_bf16 v[82:97], v[154:157], v[130:133], v[82:97]
	v_mfma_f32_32x32x16_bf16 v[66:81], v[158:161], v[130:133], v[66:81]
	v_mfma_f32_32x32x16_bf16 v[82:97], v[178:181], v[126:129], v[82:97]
	v_mfma_f32_32x32x16_bf16 v[66:81], v[182:185], v[126:129], v[66:81]
	v_mfma_f32_32x32x16_bf16 v[82:97], v[190:193], v[122:125], v[82:97]
	v_mfma_f32_32x32x16_bf16 v[66:81], v[198:201], v[122:125], v[66:81]
	ds_read_b128 v[122:125], v202 offset:256
	ds_read_b128 v[126:129], v202 offset:12544
	ds_read_b128 v[130:133], v203 offset:256
	ds_read_b128 v[154:157], v203 offset:12544
	ds_read_b128 v[158:161], v0 offset:256
	ds_read_b128 v[178:181], v0 offset:12544
	s_waitcnt lgkmcnt(0)
	v_mfma_f32_32x32x16_bf16 v[82:97], v[134:137], v[114:117], v[82:97]
	v_mfma_f32_32x32x16_bf16 v[66:81], v[138:141], v[114:117], v[66:81]
	v_mfma_f32_32x32x16_bf16 v[82:97], v[142:145], v[110:113], v[82:97]
	v_mfma_f32_32x32x16_bf16 v[66:81], v[146:149], v[110:113], v[66:81]
	v_mfma_f32_32x32x16_bf16 v[82:97], v[150:153], v[118:121], v[82:97]
	v_mfma_f32_32x32x16_bf16 v[66:81], v[186:189], v[118:121], v[66:81]
	v_mfma_f32_32x32x16_bf16 v[82:97], v[122:125], v[106:109], v[82:97]
	v_mfma_f32_32x32x16_bf16 v[66:81], v[126:129], v[106:109], v[66:81]
	v_mfma_f32_32x32x16_bf16 v[82:97], v[130:133], v[102:105], v[82:97]
	v_mfma_f32_32x32x16_bf16 v[66:81], v[154:157], v[102:105], v[66:81]
	v_mfma_f32_32x32x16_bf16 v[82:97], v[158:161], v[98:101], v[82:97]
	v_mfma_f32_32x32x16_bf16 v[66:81], v[178:181], v[98:101], v[66:81]
	v_add_u32_e32 v106, s2, v229
	v_add_u32_e32 v0, s2, v228
	v_xor_b32_e32 v107, 64, v106
	v_add_u32_e32 v0, 0, v0
	v_xor_b32_e32 v98, 32, v106
	v_add_u32_e32 v131, 0, v107
	v_xor_b32_e32 v106, 0x60, v106
	s_nop 7
	s_nop 7
	s_nop 3
	v_add_u32_e32 v130, 0, v98
	ds_read_b128 v[102:105], v0 offset:24576
	ds_read_b128 v[98:101], v130
	v_add_u32_e32 v132, 0, v106
	ds_read_b128 v[110:113], v131
	ds_read_b128 v[106:109], v132
	v_max3_f32 v114, v176, v82, v66
	s_nop 0
	v_max3_f32 v114, v114, v83, v67
	s_nop 0
	v_max3_f32 v114, v114, v84, v68
	s_nop 0
	v_max3_f32 v114, v114, v85, v69
	s_nop 0
	v_max3_f32 v114, v114, v86, v70
	s_nop 0
	v_max3_f32 v114, v114, v87, v71
	s_nop 0
	v_max3_f32 v114, v114, v88, v72
	s_nop 0
	v_max3_f32 v114, v114, v89, v73
	s_nop 0
	v_max3_f32 v114, v114, v90, v74
	s_nop 0
	v_max3_f32 v114, v114, v91, v75
	s_nop 0
	v_max3_f32 v114, v114, v92, v76
	s_nop 0
	v_max3_f32 v114, v114, v93, v77
	s_nop 0
	v_max3_f32 v114, v114, v94, v78
	s_nop 0
	v_max3_f32 v114, v114, v95, v79
	s_nop 0
	v_max3_f32 v114, v114, v96, v80
	s_nop 0
	v_max3_f32 v114, v114, v97, v81
	s_nop 0
	s_nop 1
	s_nop 0
	v_mov_b32_e32 v115, v114
	s_nop 1
	v_permlane32_swap_b32_e32 v114, v115
	v_max_f32_e32 v115, v115, v115
	v_max_f32_e32 v114, v114, v114
	v_max_f32_e32 v128, v114, v115
	v_cmp_gt_f32_e32 vcc, v128, v176
	v_mov_b32_e32 v129, v128
	v_pk_add_f32 v[126:127], v[82:83], v[128:129] neg_lo:[0,1] neg_hi:[0,1]
	v_pk_add_f32 v[124:125], v[66:67], v[128:129] neg_lo:[0,1] neg_hi:[0,1]
	v_pk_add_f32 v[122:123], v[84:85], v[128:129] neg_lo:[0,1] neg_hi:[0,1]
	v_pk_add_f32 v[120:121], v[68:69], v[128:129] neg_lo:[0,1] neg_hi:[0,1]
	v_pk_add_f32 v[118:119], v[86:87], v[128:129] neg_lo:[0,1] neg_hi:[0,1]
	v_pk_add_f32 v[116:117], v[70:71], v[128:129] neg_lo:[0,1] neg_hi:[0,1]
	v_pk_add_f32 v[114:115], v[88:89], v[128:129] neg_lo:[0,1] neg_hi:[0,1]
	v_pk_add_f32 v[88:89], v[72:73], v[128:129] neg_lo:[0,1] neg_hi:[0,1]
	v_pk_add_f32 v[86:87], v[90:91], v[128:129] neg_lo:[0,1] neg_hi:[0,1]
	v_pk_add_f32 v[84:85], v[74:75], v[128:129] neg_lo:[0,1] neg_hi:[0,1]
	v_pk_add_f32 v[82:83], v[92:93], v[128:129] neg_lo:[0,1] neg_hi:[0,1]
	v_pk_add_f32 v[74:75], v[76:77], v[128:129] neg_lo:[0,1] neg_hi:[0,1]
	v_pk_add_f32 v[72:73], v[94:95], v[128:129] neg_lo:[0,1] neg_hi:[0,1]
	v_pk_add_f32 v[70:71], v[78:79], v[128:129] neg_lo:[0,1] neg_hi:[0,1]
	v_pk_add_f32 v[68:69], v[96:97], v[128:129] neg_lo:[0,1] neg_hi:[0,1]
	v_pk_add_f32 v[66:67], v[80:81], v[128:129] neg_lo:[0,1] neg_hi:[0,1]
	s_cbranch_vccz .LBB0_1144
; __device__ __forceinline__ float exp2_(float x) { return __builtin_amdgcn_exp2f(x); }
; #define AT_RV(vf, mb) do { vf[0] = *(const LAS bf16x8*)(lds + vb + (mb) * 4096); vf[1] = *(const LAS bf16x8*)(lds + (vb ^ 32u) + (mb) * 4096); \
;                 vf[2] = *(const LAS bf16x8*)(lds + (vb ^ 64u) + (mb) * 4096); vf[3] = *(const LAS bf16x8*)(lds + (vb ^ 96u) + (mb) * 4096); } while (0)
; #define AT_PV(o, vf) do { __builtin_amdgcn_s_setprio(1); o = MFMA32(vf[0], p00, o); o = MFMA32(vf[1], p01, o); o = MFMA32(vf[2], p10, o); o = MFMA32(vf[3], p11, o); __builtin_amdgcn_s_setprio(0); } while (0)
; template <int TYPE  >
; __device__ __forceinline__ void attn_item(const Params& P, const int b, const int h, const int qt, LAS unsigned char* lds) {
;     ...
;                 if (__any(mnew > m_run)) {
;                     const float alpha = exp2_(m_run - mnew);
;                     l_run *= alpha; o0 *= alpha; o1 *= alpha; o2 *= alpha; o3 *= alpha;
;                 }
;                 l_run += rs; m_run = mnew;
;             }
;             const bf16x8 p00 = pack8(s0, 0), p01 = pack8(s0, 1), p10 = pack8(s1, 0), p11 = pack8(s1, 1);
;     ...
;             __builtin_amdgcn_sched_barrier(0);
;             AT_RV(vf1, 1); AT_PV(o0, vf0); __builtin_amdgcn_sched_barrier(0);
;             AT_RV(vf2, 2); AT_PV(o1, vf1); __builtin_amdgcn_sched_barrier(0);
;             AT_RV(vf3, 3); AT_PV(o2, vf2); __builtin_amdgcn_sched_barrier(0);
;             AT_PV(o3, vf3); __builtin_amdgcn_sched_barrier(0);
	v_sub_f32_e32 v76, v176, v128
	v_exp_f32_e32 v76, v76
	s_nop 0
	v_mul_f32_e32 v227, v227, v76
	v_pk_mul_f32 v[64:65], v[64:65], v[76:77] op_sel_hi:[1,0]
	v_pk_mul_f32 v[62:63], v[62:63], v[76:77] op_sel_hi:[1,0]
	v_pk_mul_f32 v[60:61], v[60:61], v[76:77] op_sel_hi:[1,0]
	v_pk_mul_f32 v[58:59], v[58:59], v[76:77] op_sel_hi:[1,0]
	v_pk_mul_f32 v[56:57], v[56:57], v[76:77] op_sel_hi:[1,0]
	v_pk_mul_f32 v[54:55], v[54:55], v[76:77] op_sel_hi:[1,0]
	v_pk_mul_f32 v[52:53], v[52:53], v[76:77] op_sel_hi:[1,0]
	v_pk_mul_f32 v[50:51], v[50:51], v[76:77] op_sel_hi:[1,0]
	v_pk_mul_f32 v[48:49], v[48:49], v[76:77] op_sel_hi:[1,0]
	v_pk_mul_f32 v[46:47], v[46:47], v[76:77] op_sel_hi:[1,0]
	v_pk_mul_f32 v[44:45], v[44:45], v[76:77] op_sel_hi:[1,0]
	v_pk_mul_f32 v[42:43], v[42:43], v[76:77] op_sel_hi:[1,0]
	v_pk_mul_f32 v[40:41], v[40:41], v[76:77] op_sel_hi:[1,0]
	v_pk_mul_f32 v[38:39], v[38:39], v[76:77] op_sel_hi:[1,0]
	v_pk_mul_f32 v[36:37], v[36:37], v[76:77] op_sel_hi:[1,0]
	v_pk_mul_f32 v[34:35], v[34:35], v[76:77] op_sel_hi:[1,0]
	v_pk_mul_f32 v[32:33], v[32:33], v[76:77] op_sel_hi:[1,0]
	v_pk_mul_f32 v[30:31], v[30:31], v[76:77] op_sel_hi:[1,0]
	v_pk_mul_f32 v[28:29], v[28:29], v[76:77] op_sel_hi:[1,0]
	v_pk_mul_f32 v[26:27], v[26:27], v[76:77] op_sel_hi:[1,0]
	v_pk_mul_f32 v[24:25], v[24:25], v[76:77] op_sel_hi:[1,0]
	v_pk_mul_f32 v[22:23], v[22:23], v[76:77] op_sel_hi:[1,0]
	v_pk_mul_f32 v[20:21], v[20:21], v[76:77] op_sel_hi:[1,0]
	v_pk_mul_f32 v[18:19], v[18:19], v[76:77] op_sel_hi:[1,0]
	v_pk_mul_f32 v[16:17], v[16:17], v[76:77] op_sel_hi:[1,0]
	v_pk_mul_f32 v[14:15], v[14:15], v[76:77] op_sel_hi:[1,0]
	v_pk_mul_f32 v[12:13], v[12:13], v[76:77] op_sel_hi:[1,0]
	v_pk_mul_f32 v[10:11], v[10:11], v[76:77] op_sel_hi:[1,0]
	v_pk_mul_f32 v[8:9], v[8:9], v[76:77] op_sel_hi:[1,0]
	v_pk_mul_f32 v[6:7], v[6:7], v[76:77] op_sel_hi:[1,0]
	v_pk_mul_f32 v[4:5], v[4:5], v[76:77] op_sel_hi:[1,0]
	v_pk_mul_f32 v[2:3], v[2:3], v[76:77] op_sel_hi:[1,0]
.LBB0_1144:
	v_exp_f32_e32 v76, v126
	v_exp_f32_e32 v77, v127
	v_exp_f32_e32 v78, v124
	v_exp_f32_e32 v79, v125
	v_exp_f32_e32 v80, v122
	v_exp_f32_e32 v81, v123
	v_exp_f32_e32 v90, v120
	v_exp_f32_e32 v91, v121
	v_exp_f32_e32 v96, v118
	v_exp_f32_e32 v97, v119
	v_exp_f32_e32 v116, v116
	v_exp_f32_e32 v117, v117
	v_exp_f32_e32 v114, v114
	v_exp_f32_e32 v115, v115
	v_exp_f32_e32 v88, v88
	v_exp_f32_e32 v89, v89
	v_pk_add_f32 v[92:93], v[76:77], v[78:79]
	v_pk_add_f32 v[94:95], v[80:81], v[90:91]
	v_pk_add_f32 v[92:93], v[92:93], 0 op_sel_hi:[1,0]
	v_exp_f32_e32 v86, v86
	v_pk_add_f32 v[92:93], v[92:93], v[94:95]
	v_pk_add_f32 v[94:95], v[96:97], v[116:117]
	v_exp_f32_e32 v87, v87
	v_exp_f32_e32 v84, v84
	v_exp_f32_e32 v85, v85
	v_pk_add_f32 v[92:93], v[92:93], v[94:95]
	v_pk_add_f32 v[94:95], v[114:115], v[88:89]
	v_exp_f32_e32 v82, v82
	v_exp_f32_e32 v83, v83
	v_exp_f32_e32 v118, v74
	v_exp_f32_e32 v119, v75
	v_pk_add_f32 v[74:75], v[92:93], v[94:95]
	v_exp_f32_e32 v72, v72
	v_exp_f32_e32 v73, v73
	v_exp_f32_e32 v94, v70
	v_exp_f32_e32 v95, v71
	v_exp_f32_e32 v120, v68
	v_exp_f32_e32 v121, v69
	v_exp_f32_e32 v122, v66
	v_exp_f32_e32 v123, v67
	v_pk_add_f32 v[92:93], v[86:87], v[84:85]
	v_pk_add_f32 v[68:69], v[72:73], v[94:95]
	v_pk_add_f32 v[74:75], v[74:75], v[92:93]
	v_pk_add_f32 v[92:93], v[82:83], v[118:119]
	v_cvt_pk_bf16_f32 v70, v86, v87
	v_pk_add_f32 v[66:67], v[74:75], v[92:93]
	v_cvt_pk_bf16_f32 v71, v82, v83
	v_pk_add_f32 v[66:67], v[66:67], v[68:69]
	v_pk_add_f32 v[68:69], v[120:121], v[122:123]
	v_cvt_pk_bf16_f32 v72, v72, v73
	v_pk_add_f32 v[66:67], v[66:67], v[68:69]
	v_cvt_pk_bf16_f32 v68, v96, v97
	v_add_f32_e32 v66, v66, v67
	v_add_f32_e32 v227, v66, v227
	v_cvt_pk_bf16_f32 v66, v76, v77
	v_cvt_pk_bf16_f32 v67, v80, v81
	v_cvt_pk_bf16_f32 v69, v114, v115
	v_cvt_pk_bf16_f32 v73, v120, v121
	v_cvt_pk_bf16_f32 v74, v78, v79
	v_cvt_pk_bf16_f32 v75, v90, v91
	v_cvt_pk_bf16_f32 v76, v116, v117
	v_cvt_pk_bf16_f32 v77, v88, v89
	v_cvt_pk_bf16_f32 v78, v84, v85
	v_cvt_pk_bf16_f32 v79, v118, v119
	v_cvt_pk_bf16_f32 v80, v94, v95
	v_cvt_pk_bf16_f32 v81, v122, v123
	ds_read_b128 v[82:85], v0 offset:28672
	ds_read_b128 v[86:89], v130 offset:4096
	ds_read_b128 v[90:93], v131 offset:4096
	ds_read_b128 v[94:97], v132 offset:4096
	s_waitcnt lgkmcnt(0)
	v_mfma_f32_32x32x16_bf16 v[50:65], v[102:105], v[66:69], v[50:65]
	v_mfma_f32_32x32x16_bf16 v[50:65], v[98:101], v[70:73], v[50:65]
	v_mfma_f32_32x32x16_bf16 v[50:65], v[110:113], v[74:77], v[50:65]
	v_mfma_f32_32x32x16_bf16 v[50:65], v[106:109], v[78:81], v[50:65]
	ds_read_b128 v[98:101], v0 offset:32768
	ds_read_b128 v[102:105], v130 offset:8192
	ds_read_b128 v[106:109], v131 offset:8192
	ds_read_b128 v[110:113], v132 offset:8192
	v_mfma_f32_32x32x16_bf16 v[34:49], v[82:85], v[66:69], v[34:49]
	v_mfma_f32_32x32x16_bf16 v[34:49], v[86:89], v[70:73], v[34:49]
	v_mfma_f32_32x32x16_bf16 v[34:49], v[90:93], v[74:77], v[34:49]
	v_mfma_f32_32x32x16_bf16 v[34:49], v[94:97], v[78:81], v[34:49]
	ds_read_b128 v[82:85], v0 offset:36864
	ds_read_b128 v[86:89], v130 offset:12288
	ds_read_b128 v[90:93], v131 offset:12288
	ds_read_b128 v[94:97], v132 offset:12288
	s_waitcnt lgkmcnt(0)
	v_mfma_f32_32x32x16_bf16 v[18:33], v[98:101], v[66:69], v[18:33]
	v_mfma_f32_32x32x16_bf16 v[18:33], v[102:105], v[70:73], v[18:33]
	v_mfma_f32_32x32x16_bf16 v[18:33], v[106:109], v[74:77], v[18:33]
	v_mfma_f32_32x32x16_bf16 v[18:33], v[110:113], v[78:81], v[18:33]
	v_mfma_f32_32x32x16_bf16 v[2:17], v[82:85], v[66:69], v[2:17]
	v_mfma_f32_32x32x16_bf16 v[2:17], v[86:89], v[70:73], v[2:17]
	v_mfma_f32_32x32x16_bf16 v[2:17], v[90:93], v[74:77], v[2:17]
	v_mfma_f32_32x32x16_bf16 v[2:17], v[94:97], v[78:81], v[2:17]

; #define LAS __attribute__((address_space(3)))
; __device__ __forceinline__ f32x2 pk_sub(f32x2 a, f32x2 b) { f32x2 r; asm("v_pk_add_f32 %0, %1, %2 neg_lo:[0,1] neg_hi:[0,1]" : "=v"(r) : "v"(a), "v"(b)); return r; }
; template <int TYPE  >
; __device__ __forceinline__ void attn_item(const Params& P, const int b, const int h, const int qt, LAS unsigned char* lds) {
;     ...
;                 if (TYPE == 1) { const LAS float* fb = (const LAS float*)(lds + so + KREG + VREG + wid * 256) + 8 * hh;
; #pragma unroll
;                     for (int j = 0; j < 8; ++j) {
;                         const f32x2 b0 = *(const LAS f32x2*)(fb + 16 * (j >> 2) + 2 * (j & 3)), b1 = *(const LAS f32x2*)(fb + 32 + 16 * (j >> 2) + 2 * (j & 3));
;                         const f32x2 x0 = pk_sub((f32x2){s0[2 * j], s0[2 * j + 1]}, b0), x1 = pk_sub((f32x2){s1[2 * j], s1[2 * j + 1]}, b1);
;                         s0[2 * j] = x0[0]; s0[2 * j + 1] = x0[1]; s1[2 * j] = x1[0]; s1[2 * j + 1] = x1[1]; }
;                     if (diag) {
; #pragma unroll
;                         for (int i = 0; i < 16; ++i) { const int key = key0 + 16 * (i >> 3) + (i & 7); if (key > tq) s0[i] = -1e30f; if (key + 32 > tq) s1[i] = -1e30f; } } }
.LBB0_1153:
	s_cmp_gt_i32 s16, s11
	s_cbranch_scc1 .Lfx_skipdma
	v_add_u32_e32 v0, s13, v187
	v_add_u32_e32 v70, 0, v0
	v_xad_u32 v74, v0, 32, 0
	ds_read_b128 v[66:69], v70
	ds_read_b128 v[70:73], v70 offset:8192
	ds_read_b128 v[130:133], v74
	ds_read_b128 v[134:137], v74 offset:8192
	v_xad_u32 v74, v0, 64, 0
	ds_read_b128 v[138:141], v74
	ds_read_b128 v[142:145], v74 offset:8192
	v_xor_b32_e32 v74, 0x60, v0
	v_add_u32_e32 v74, 0, v74
	ds_read_b128 v[156:159], v74
	ds_read_b128 v[176:179], v74 offset:8192
	v_xor_b32_e32 v74, 0x80, v0
	v_add_u32_e32 v74, 0, v74
	ds_read_b128 v[180:183], v74
	ds_read_b128 v[198:201], v74 offset:8192
	v_xor_b32_e32 v74, 0xa0, v0
	v_add_u32_e32 v74, 0, v74
	ds_read_b128 v[202:205], v74
	ds_read_b128 v[226:229], v74 offset:8192
	v_xor_b32_e32 v74, 0xc0, v0
	v_xor_b32_e32 v0, 0xe0, v0
	v_add_u32_e32 v74, 0, v74
	v_add_u32_e32 v0, 0, v0
	ds_read_b128 v[230:233], v74
	ds_read_b128 v[234:237], v74 offset:8192
	ds_read_b128 v[238:241], v0
	ds_read_b128 v[242:245], v0 offset:8192
	s_waitcnt lgkmcnt(0)
	v_mfma_f32_32x32x16_bf16 v[82:97], v[66:69], v[98:101], 0
	v_mfma_f32_32x32x16_bf16 v[66:81], v[70:73], v[98:101], 0
	v_mfma_f32_32x32x16_bf16 v[82:97], v[130:133], v[102:105], v[82:97]
	v_mfma_f32_32x32x16_bf16 v[66:81], v[134:137], v[102:105], v[66:81]
	v_mfma_f32_32x32x16_bf16 v[82:97], v[138:141], v[106:109], v[82:97]
	v_mfma_f32_32x32x16_bf16 v[66:81], v[142:145], v[106:109], v[66:81]
	v_mfma_f32_32x32x16_bf16 v[82:97], v[156:159], v[110:113], v[82:97]
	v_mfma_f32_32x32x16_bf16 v[66:81], v[176:179], v[110:113], v[66:81]
	v_mfma_f32_32x32x16_bf16 v[82:97], v[180:183], v[114:117], v[82:97]
	v_mfma_f32_32x32x16_bf16 v[66:81], v[198:201], v[114:117], v[66:81]
	v_mfma_f32_32x32x16_bf16 v[82:97], v[202:205], v[118:121], v[82:97]
	v_mfma_f32_32x32x16_bf16 v[66:81], v[226:229], v[118:121], v[66:81]
	v_mfma_f32_32x32x16_bf16 v[82:97], v[230:233], v[122:125], v[82:97]
	v_mfma_f32_32x32x16_bf16 v[66:81], v[234:237], v[122:125], v[66:81]
	v_mfma_f32_32x32x16_bf16 v[82:97], v[238:241], v[126:129], v[82:97]
	v_mfma_f32_32x32x16_bf16 v[66:81], v[242:245], v[126:129], v[66:81]
	v_add_u32_e32 v138, s13, v190
	v_add_u32_e32 v0, s13, v189
	v_xor_b32_e32 v139, 64, v138
	v_add_u32_e32 v0, 0, v0
	v_xor_b32_e32 v130, 32, v138
	v_add_u32_e32 v194, 0, v139
	v_xor_b32_e32 v138, 0x60, v138
	s_nop 7
	s_nop 7
	s_nop 3
	v_add_u32_e32 v193, 0, v130
	ds_read_b128 v[134:137], v0 offset:16384
	ds_read_b128 v[130:133], v193
	v_add_u32_e32 v195, 0, v138
	ds_read_b128 v[142:145], v194
	ds_read_b128 v[138:141], v195
	v_add_u32_e32 v156, s13, v191
	v_add_u32_e32 v184, 0x8000, v156
	ds_read2_b64 v[198:201], v184 offset1:1
	ds_read2_b64 v[202:205], v184 offset0:2 offset1:3
	ds_read2_b64 v[226:229], v184 offset0:16 offset1:17
	ds_read2_b64 v[230:233], v184 offset0:18 offset1:19
	ds_read2_b64 v[234:237], v184 offset0:8 offset1:9
	ds_read2_b64 v[238:241], v184 offset0:24 offset1:25
	ds_read2_b64 v[242:245], v184 offset0:10 offset1:11
	ds_read2_b64 v[246:249], v184 offset0:26 offset1:27
	s_cmp_lg_u32 s11, s16
	s_waitcnt lgkmcnt(0)
	v_pk_add_f32 v[82:83], v[82:83], v[198:199] neg_lo:[0,1] neg_hi:[0,1]
	v_pk_add_f32 v[158:159], v[66:67], v[226:227] neg_lo:[0,1] neg_hi:[0,1]
	v_pk_add_f32 v[156:157], v[84:85], v[200:201] neg_lo:[0,1] neg_hi:[0,1]
	v_pk_add_f32 v[84:85], v[68:69], v[228:229] neg_lo:[0,1] neg_hi:[0,1]
	v_pk_add_f32 v[68:69], v[86:87], v[202:203] neg_lo:[0,1] neg_hi:[0,1]
	v_pk_add_f32 v[86:87], v[88:89], v[204:205] neg_lo:[0,1] neg_hi:[0,1]
	v_pk_add_f32 v[160:161], v[70:71], v[230:231] neg_lo:[0,1] neg_hi:[0,1]
	v_pk_add_f32 v[70:71], v[72:73], v[232:233] neg_lo:[0,1] neg_hi:[0,1]
	v_pk_add_f32 v[72:73], v[90:91], v[234:235] neg_lo:[0,1] neg_hi:[0,1]
	v_pk_add_f32 v[88:89], v[92:93], v[236:237] neg_lo:[0,1] neg_hi:[0,1]
	v_pk_add_f32 v[90:91], v[74:75], v[238:239] neg_lo:[0,1] neg_hi:[0,1]
	v_pk_add_f32 v[74:75], v[76:77], v[240:241] neg_lo:[0,1] neg_hi:[0,1]
	v_pk_add_f32 v[76:77], v[94:95], v[242:243] neg_lo:[0,1] neg_hi:[0,1]
	v_pk_add_f32 v[94:95], v[78:79], v[246:247] neg_lo:[0,1] neg_hi:[0,1]
	v_pk_add_f32 v[92:93], v[96:97], v[244:245] neg_lo:[0,1] neg_hi:[0,1]
	v_pk_add_f32 v[78:79], v[80:81], v[248:249] neg_lo:[0,1] neg_hi:[0,1]
	s_cbranch_scc1 .LBB0_1156
	v_cndmask_b32_e64 v66, v82, v223, s[38:39]
	v_cndmask_b32_e64 v158, v158, v223, s[40:41]
	v_cndmask_b32_e64 v82, v66, v82, s[42:43]
	v_cndmask_b32_e64 v83, v223, v83, s[42:43]
	v_cndmask_b32_e64 v159, v159, v223, s[44:45]
	v_cndmask_b32_e64 v156, v156, v223, s[46:47]
	v_cndmask_b32_e64 v84, v84, v223, s[48:49]
	v_cndmask_b32_e64 v157, v157, v223, s[50:51]
	v_cndmask_b32_e64 v85, v85, v223, s[52:53]
	v_cndmask_b32_e64 v68, v68, v223, s[54:55]
	v_cndmask_b32_e64 v160, v160, v223, s[56:57]
	v_cndmask_b32_e64 v69, v69, v223, s[58:59]
	v_cndmask_b32_e64 v161, v161, v223, s[60:61]
	v_cndmask_b32_e64 v86, v86, v223, s[62:63]
	v_cndmask_b32_e64 v70, v70, v223, s[64:65]
	v_cndmask_b32_e64 v87, v87, v223, s[66:67]
	v_cndmask_b32_e64 v71, v71, v223, s[68:69]
	v_cndmask_b32_e64 v72, v72, v223, s[70:71]
	v_cndmask_b32_e64 v90, v90, v223, s[72:73]
	v_cndmask_b32_e64 v73, v73, v223, s[74:75]
	v_cndmask_b32_e64 v91, v91, v223, s[76:77]
	v_cndmask_b32_e64 v88, v88, v223, s[78:79]
	v_cndmask_b32_e64 v74, v74, v223, s[4:5]
	v_cndmask_b32_e64 v89, v89, v223, s[80:81]
	v_cndmask_b32_e64 v75, v75, v223, s[82:83]
	v_cndmask_b32_e64 v76, v76, v223, s[6:7]
	v_cndmask_b32_e64 v94, v94, v223, s[84:85]
	v_cndmask_b32_e64 v77, v77, v223, s[86:87]
	v_cndmask_b32_e64 v95, v95, v223, s[88:89]
	v_cndmask_b32_e64 v92, v92, v223, s[90:91]
	v_cndmask_b32_e64 v78, v78, v223, s[92:93]
	v_cndmask_b32_e64 v93, v93, v223, s[94:95]
	v_cndmask_b32_e64 v79, v79, v223, s[96:97]

; __device__ __forceinline__ float exp2_(float x) { return __builtin_amdgcn_exp2f(x); }
; __device__ __forceinline__ f32x2 pk_sub(f32x2 a, f32x2 b) { f32x2 r; asm("v_pk_add_f32 %0, %1, %2 neg_lo:[0,1] neg_hi:[0,1]" : "=v"(r) : "v"(a), "v"(b)); return r; }
; #define AT_RV(vf, mb) do { vf[0] = *(const LAS bf16x8*)(lds + vb + (mb) * 4096); vf[1] = *(const LAS bf16x8*)(lds + (vb ^ 32u) + (mb) * 4096); \
;                 vf[2] = *(const LAS bf16x8*)(lds + (vb ^ 64u) + (mb) * 4096); vf[3] = *(const LAS bf16x8*)(lds + (vb ^ 96u) + (mb) * 4096); } while (0)
; #define AT_PV(o, vf) do { __builtin_amdgcn_s_setprio(1); o = MFMA32(vf[0], p00, o); o = MFMA32(vf[1], p01, o); o = MFMA32(vf[2], p10, o); o = MFMA32(vf[3], p11, o); __builtin_amdgcn_s_setprio(0); } while (0)
; template <int TYPE  >
; __device__ __forceinline__ void attn_item(const Params& P, const int b, const int h, const int qt, LAS unsigned char* lds) {
;     ...
;                 for (int j = 0; j < 8; ++j) { const f32x2 x0 = pk_sub((f32x2){s0[2 * j], s0[2 * j + 1]}, mm), x1 = pk_sub((f32x2){s1[2 * j], s1[2 * j + 1]}, mm);
;                     s0[2 * j] = exp2_(x0[0]); s0[2 * j + 1] = exp2_(x0[1]); s1[2 * j] = exp2_(x1[0]); s1[2 * j + 1] = exp2_(x1[1]);
;                     rs2 += (f32x2){s0[2 * j], s0[2 * j + 1]} + (f32x2){s1[2 * j], s1[2 * j + 1]}; }
;                 const float rs = rs2[0] + rs2[1];
;                 if (__any(mnew > m_run)) {
;                     const float alpha = exp2_(m_run - mnew);
;                     l_run *= alpha; o0 *= alpha; o1 *= alpha; o2 *= alpha; o3 *= alpha;
;                 }
;                 l_run += rs; m_run = mnew;
;             }
;             const bf16x8 p00 = pack8(s0, 0), p01 = pack8(s0, 1), p10 = pack8(s1, 0), p11 = pack8(s1, 1);
;     ...
;             __builtin_amdgcn_sched_barrier(0);
;             AT_RV(vf1, 1); AT_PV(o0, vf0); __builtin_amdgcn_sched_barrier(0);
;             AT_RV(vf2, 2); AT_PV(o1, vf1); __builtin_amdgcn_sched_barrier(0);
;             AT_RV(vf3, 3); AT_PV(o2, vf2); __builtin_amdgcn_sched_barrier(0);
;             AT_PV(o3, vf3); __builtin_amdgcn_sched_barrier(0);
.LBB0_1158:
	v_exp_f32_e32 v76, v184
	v_exp_f32_e32 v77, v185
	v_exp_f32_e32 v78, v182
	v_exp_f32_e32 v79, v183
	v_exp_f32_e32 v88, v180
	v_exp_f32_e32 v89, v181
	v_exp_f32_e32 v90, v178
	v_exp_f32_e32 v91, v179
	v_exp_f32_e32 v160, v176
	v_exp_f32_e32 v161, v177
	v_exp_f32_e32 v158, v158
	v_exp_f32_e32 v159, v159
	v_exp_f32_e32 v156, v156
	v_exp_f32_e32 v157, v157
	v_exp_f32_e32 v96, v96
	v_exp_f32_e32 v97, v97
	v_pk_add_f32 v[92:93], v[76:77], v[78:79]
	v_pk_add_f32 v[94:95], v[88:89], v[90:91]
	v_pk_add_f32 v[92:93], v[92:93], 0 op_sel_hi:[1,0]
	v_exp_f32_e32 v86, v86
	v_pk_add_f32 v[92:93], v[92:93], v[94:95]
	v_pk_add_f32 v[94:95], v[160:161], v[158:159]
	v_exp_f32_e32 v87, v87
	v_exp_f32_e32 v84, v84
	v_exp_f32_e32 v85, v85
	v_pk_add_f32 v[92:93], v[92:93], v[94:95]
	v_pk_add_f32 v[94:95], v[156:157], v[96:97]
	v_exp_f32_e32 v82, v82
	v_exp_f32_e32 v83, v83
	v_exp_f32_e32 v176, v80
	v_exp_f32_e32 v177, v81
	v_pk_add_f32 v[80:81], v[92:93], v[94:95]
	v_exp_f32_e32 v74, v74
	v_exp_f32_e32 v75, v75
	v_exp_f32_e32 v94, v72
	v_exp_f32_e32 v95, v73
	v_exp_f32_e32 v178, v70
	v_exp_f32_e32 v179, v71
	v_exp_f32_e32 v180, v68
	v_exp_f32_e32 v181, v69
	v_pk_add_f32 v[92:93], v[86:87], v[84:85]
	v_pk_add_f32 v[70:71], v[74:75], v[94:95]
	v_pk_add_f32 v[80:81], v[80:81], v[92:93]
	v_pk_add_f32 v[92:93], v[82:83], v[176:177]
	v_cvt_pk_bf16_f32 v72, v86, v87
	v_pk_add_f32 v[68:69], v[80:81], v[92:93]
	v_cvt_pk_bf16_f32 v73, v82, v83
	v_pk_add_f32 v[68:69], v[68:69], v[70:71]
	v_pk_add_f32 v[70:71], v[178:179], v[180:181]
	v_cvt_pk_bf16_f32 v74, v74, v75
	v_pk_add_f32 v[68:69], v[68:69], v[70:71]
	v_cvt_pk_bf16_f32 v70, v160, v161
	v_add_f32_e32 v67, v68, v69
	v_add_f32_e32 v192, v67, v192
	v_cvt_pk_bf16_f32 v68, v76, v77
	v_cvt_pk_bf16_f32 v69, v88, v89
	v_cvt_pk_bf16_f32 v71, v156, v157
	v_cvt_pk_bf16_f32 v75, v178, v179
	v_cvt_pk_bf16_f32 v76, v78, v79
	v_cvt_pk_bf16_f32 v77, v90, v91
	v_cvt_pk_bf16_f32 v78, v158, v159
	v_cvt_pk_bf16_f32 v79, v96, v97
	v_cvt_pk_bf16_f32 v80, v84, v85
	v_cvt_pk_bf16_f32 v81, v176, v177
	v_cvt_pk_bf16_f32 v82, v94, v95
	v_cvt_pk_bf16_f32 v83, v180, v181
	ds_read_b128 v[84:87], v0 offset:20480
	ds_read_b128 v[88:91], v193 offset:4096
	ds_read_b128 v[92:95], v194 offset:4096
	ds_read_b128 v[156:159], v195 offset:4096
	v_mfma_f32_32x32x16_bf16 v[50:65], v[134:137], v[68:71], v[50:65]
	v_mfma_f32_32x32x16_bf16 v[50:65], v[130:133], v[72:75], v[50:65]
	v_mfma_f32_32x32x16_bf16 v[50:65], v[142:145], v[76:79], v[50:65]
	v_mfma_f32_32x32x16_bf16 v[50:65], v[138:141], v[80:83], v[50:65]
	s_add_i32 s8, s16, 2
	s_cmp_ge_u32 s8, s36
	s_cbranch_scc1 .Lfx_nodma
	s_add_i32 s8, s3, s14
	v_lshl_add_u64 v[226:227], s[30:31], 0, v[154:155]
	s_mov_b32 m0, s8
	s_nop 0
	global_load_lds_dwordx4 v[226:227], off
	s_add_i32 m0, s8, 0x400
	s_add_i32 s8, s14, 0
	v_lshl_add_u64 v[226:227], s[30:31], 0, v[152:153]
	s_add_i32 s9, s8, s2
	global_load_lds_dwordx4 v[226:227], off
	s_add_i32 m0, s9, 0x4000
	v_lshl_add_u64 v[226:227], s[30:31], 0, v[150:151]
	global_load_lds_dwordx4 v[226:227], off
	v_lshl_add_u64 v[226:227], s[30:31], 0, v[148:149]
	s_add_i32 m0, s9, 0x4400
	s_add_i32 s8, s8, s12
	global_load_lds_dwordx4 v[226:227], off
	v_lshl_add_u64 v[226:227], s[30:31], 0, v[146:147]
	s_add_i32 m0, s8, 0x8000
	s_nop 0
	global_load_lds_dword v[226:227], off
.Lfx_nodma:
	ds_read_b128 v[130:133], v0 offset:24576
	ds_read_b128 v[134:137], v193 offset:8192
	ds_read_b128 v[138:141], v194 offset:8192
	ds_read_b128 v[142:145], v195 offset:8192
	s_waitcnt lgkmcnt(0)
	v_mfma_f32_32x32x16_bf16 v[34:49], v[84:87], v[68:71], v[34:49]
	v_mfma_f32_32x32x16_bf16 v[34:49], v[88:91], v[72:75], v[34:49]
	v_mfma_f32_32x32x16_bf16 v[34:49], v[92:95], v[76:79], v[34:49]
	v_mfma_f32_32x32x16_bf16 v[34:49], v[156:159], v[80:83], v[34:49]
	ds_read_b128 v[84:87], v0 offset:28672
	ds_read_b128 v[88:91], v193 offset:12288
	ds_read_b128 v[92:95], v194 offset:12288
	ds_read_b128 v[156:159], v195 offset:12288
	v_mfma_f32_32x32x16_bf16 v[18:33], v[130:133], v[68:71], v[18:33]
	v_mfma_f32_32x32x16_bf16 v[18:33], v[134:137], v[72:75], v[18:33]
	v_mfma_f32_32x32x16_bf16 v[18:33], v[138:141], v[76:79], v[18:33]
	v_mfma_f32_32x32x16_bf16 v[18:33], v[142:145], v[80:83], v[18:33]
	s_waitcnt lgkmcnt(0)
	v_mfma_f32_32x32x16_bf16 v[2:17], v[84:87], v[68:71], v[2:17]
	v_mfma_f32_32x32x16_bf16 v[2:17], v[88:91], v[72:75], v[2:17]
	v_mfma_f32_32x32x16_bf16 v[2:17], v[92:95], v[76:79], v[2:17]
	v_mfma_f32_32x32x16_bf16 v[2:17], v[156:159], v[80:83], v[2:17]
	s_branch .LBB0_1160

; __device__ __forceinline__ void phase_attn(const Params& P, LAS unsigned char* lds) {
;     ...
;     asm volatile("s_waitcnt vmcnt(0)" ::: "memory"); __syncthreads();
; }
; __device__ __forceinline__ void xcd_barrier(const XcdBarrier& b) {
;     asm volatile("s_waitcnt vmcnt(0)" ::: "memory");
;     __syncthreads();
;     if (threadIdx.x == 0) {
;         unsigned* bar = b.bar;
;         __builtin_amdgcn_s_waitcnt(0);
;         unsigned nloc = b.st[0], nx = b.st[1];
;         if (nloc == 0u) { xcd_barrier_complete(bar, b.x, nloc, nx); b.st[0] = nloc; b.st[1] = nx; }
.LBB0_1162:
	s_setprio 0
	s_waitcnt vmcnt(0)
	v_readlane_b32 s0, v254, 3
	s_add_i32 s16, s0, 5
	s_waitcnt lgkmcnt(0)
	s_cmp_ge_i32 s16, s91
	s_waitcnt vmcnt(0)
	s_barrier
	s_cbranch_scc1 .LBB0_1174
	s_waitcnt vmcnt(0)
	s_barrier
	s_mov_b64 s[0:1], exec
	v_readlane_b32 s2, v253, 1
	v_readlane_b32 s3, v253, 2
	v_readlane_b32 s36, v254, 0
	s_and_b64 s[2:3], s[0:1], s[2:3]
	v_readlane_b32 s28, v253, 63
	v_readlane_b32 s37, v254, 1
	s_mov_b64 exec, s[2:3]
	s_cbranch_execz .LBB0_1216
	v_readlane_b32 s2, v253, 53
	s_waitcnt vmcnt(0) expcnt(0) lgkmcnt(0)
	s_nop 0
	v_mov_b32_e32 v0, s2
	ds_read_b32 v3, v0
	v_readlane_b32 s2, v253, 54
	s_waitcnt lgkmcnt(0)
	v_cmp_ne_u32_e32 vcc, 0, v3
	v_mov_b32_e32 v0, s2
	ds_read_b32 v2, v0
	s_cbranch_vccnz .LBB0_1180
	s_mov_b32 s8, 1
	s_branch .LBB0_1167

; __global__ void __launch_bounds__(512, 2) mega(Params P0) {
	.amdhsa_kernel _Z4mega6Params
		.amdhsa_group_segment_fixed_size 0
		.amdhsa_private_segment_fixed_size 0
		.amdhsa_kernarg_size 400
		.amdhsa_user_sgpr_count 2
		.amdhsa_user_sgpr_dispatch_ptr 0
		.amdhsa_user_sgpr_queue_ptr 0
		.amdhsa_user_sgpr_kernarg_segment_ptr 1
		.amdhsa_user_sgpr_dispatch_id 0
		.amdhsa_user_sgpr_kernarg_preload_length 0
		.amdhsa_user_sgpr_kernarg_preload_offset 0
		.amdhsa_user_sgpr_private_segment_size 0
		.amdhsa_uses_dynamic_stack 0
		.amdhsa_enable_private_segment 0
		.amdhsa_system_sgpr_workgroup_id_x 1
		.amdhsa_system_sgpr_workgroup_id_y 0
		.amdhsa_system_sgpr_workgroup_id_z 0
		.amdhsa_system_sgpr_workgroup_info 0
		.amdhsa_system_vgpr_workitem_id 2
		.amdhsa_next_free_vgpr 256
		.amdhsa_next_free_sgpr 102
		.amdhsa_accum_offset 256
		.amdhsa_reserve_vcc 1
		.amdhsa_float_round_mode_32 0
		.amdhsa_float_round_mode_16_64 0
		.amdhsa_float_denorm_mode_32 3
		.amdhsa_float_denorm_mode_16_64 3
		.amdhsa_dx10_clamp 1
		.amdhsa_ieee_mode 1
		.amdhsa_fp16_overflow 0
		.amdhsa_tg_split 0
		.amdhsa_exception_fp_ieee_invalid_op 0
		.amdhsa_exception_fp_denorm_src 0
		.amdhsa_exception_fp_ieee_div_zero 0
		.amdhsa_exception_fp_ieee_overflow 0
		.amdhsa_exception_fp_ieee_underflow 0
		.amdhsa_exception_fp_ieee_inexact 0
		.amdhsa_exception_int_div_zero 0
	.end_amdhsa_kernel

; __global__ void __launch_bounds__(512, 2) mega(Params P0) {
amdhsa.kernels:
  - .agpr_count:     0
    .args:
      - .offset:         0
        .size:           144
        .value_kind:     by_value
      - .offset:         144
        .size:           4
        .value_kind:     hidden_block_count_x
      - .offset:         148
        .size:           4
        .value_kind:     hidden_block_count_y
      - .offset:         152
        .size:           4
        .value_kind:     hidden_block_count_z
      - .offset:         156
        .size:           2
        .value_kind:     hidden_group_size_x
      - .offset:         158
        .size:           2
        .value_kind:     hidden_group_size_y
      - .offset:         160
        .size:           2
        .value_kind:     hidden_group_size_z
      - .offset:         162
        .size:           2
        .value_kind:     hidden_remainder_x
      - .offset:         164
        .size:           2
        .value_kind:     hidden_remainder_y
      - .offset:         166
        .size:           2
        .value_kind:     hidden_remainder_z
      - .offset:         184
        .size:           8
        .value_kind:     hidden_global_offset_x
      - .offset:         192
        .size:           8
        .value_kind:     hidden_global_offset_y
      - .offset:         200
        .size:           8
        .value_kind:     hidden_global_offset_z
      - .offset:         208
        .size:           2
        .value_kind:     hidden_grid_dims
      - .offset:         232
        .size:           8
        .value_kind:     hidden_multigrid_sync_arg
      - .offset:         264
        .size:           4
        .value_kind:     hidden_dynamic_lds_size
    .group_segment_fixed_size: 0
    .kernarg_segment_align: 8
    .kernarg_segment_size: 400
    .language:       OpenCL C
    .language_version:
      - 2
      - 0
    .max_flat_workgroup_size: 512
    .name:           _Z4mega6Params
    .private_segment_fixed_size: 0
    .sgpr_count:     108
    .sgpr_spill_count: 175
    .symbol:         _Z4mega6Params.kd
    .uniform_work_group_size: 1
    .uses_dynamic_stack: false
    .vgpr_count:     256
    .vgpr_spill_count: 0
    .wavefront_size: 64
